# EpiGU rstd loads prefetched in last K-iteration (rows 0-5 at SP2(t), rows 6-7 at SP2(t+1)) in both P3 instances; conditional vmcnt
# speedup vs baseline: 1.0042x; 1.0042x over previous
.LBB0_1083:
	s_add_u32 s24, s22, 0xfffc0080
	s_addc_u32 s25, s23, -1
	s_add_i32 s54, 0, 0x10000
	s_cmp_eq_u32 s53, 12
	s_cselect_b32 s27, s15, s25
	s_cselect_b32 s26, s49, s24
	v_add_u32_e32 v140, s54, v141
	s_cselect_b32 s25, s13, s52
	s_cselect_b32 s24, s50, s51
	s_add_i32 s56, 0, 0x14000
	ds_read_b128 v[144:147], v140
	ds_read_b128 v[148:151], v140 offset:1024
	ds_read_b128 v[152:155], v140 offset:2048
	ds_read_b128 v[156:159], v140 offset:3072
	v_add_u32_e32 v140, s56, v141
	ds_read_b128 v[160:163], v140
	ds_read_b128 v[164:167], v140 offset:1024
	ds_read_b128 v[168:171], v140 offset:2048
	ds_read_b128 v[172:175], v140 offset:3072
	v_lshl_add_u64 v[196:197], s[22:23], 0, v[136:137]
	s_add_i32 m0, s38, 0xc000
	ds_read_b128 v[176:179], v143
	ds_read_b128 v[180:183], v143 offset:1024
	ds_read_b128 v[184:187], v143 offset:2048
	ds_read_b128 v[188:191], v143 offset:3072
	ds_read_b128 v[192:195], v143 offset:4096
	ds_read_b128 v[202:205], v143 offset:5120
	ds_read_b128 v[214:217], v143 offset:6144
	ds_read_b128 v[224:227], v143 offset:7168
	global_load_lds_dwordx4 v[196:197], off
	v_lshl_add_u64 v[196:197], s[22:23], 0, v[138:139]
	s_add_i32 m0, s38, 0xe000
	s_nop 0
	global_load_lds_dwordx4 v[196:197], off
	s_waitcnt vmcnt(8)
	s_waitcnt lgkmcnt(0)
	s_barrier
	s_setprio 1
	s_waitcnt lgkmcnt(0)
	v_mfma_f32_16x16x32_bf16 v[126:129], v[144:147], v[176:179], v[126:129]
	v_mfma_f32_16x16x32_bf16 v[118:121], v[152:155], v[176:179], v[118:121]
	v_mfma_f32_16x16x32_bf16 v[110:113], v[144:147], v[184:187], v[110:113]
	v_mfma_f32_16x16x32_bf16 v[102:105], v[152:155], v[184:187], v[102:105]
	v_mfma_f32_16x16x32_bf16 v[94:97], v[144:147], v[192:195], v[94:97]
	v_mfma_f32_16x16x32_bf16 v[86:89], v[152:155], v[192:195], v[86:89]
	v_mfma_f32_16x16x32_bf16 v[78:81], v[144:147], v[214:217], v[78:81]
	v_mfma_f32_16x16x32_bf16 v[70:73], v[152:155], v[214:217], v[70:73]
	v_mfma_f32_16x16x32_bf16 v[126:129], v[148:151], v[180:183], v[126:129]
	v_mfma_f32_16x16x32_bf16 v[118:121], v[156:159], v[180:183], v[118:121]
	v_mfma_f32_16x16x32_bf16 v[110:113], v[148:151], v[188:191], v[110:113]
	v_mfma_f32_16x16x32_bf16 v[102:105], v[156:159], v[188:191], v[102:105]
	v_mfma_f32_16x16x32_bf16 v[94:97], v[148:151], v[202:205], v[94:97]
	v_mfma_f32_16x16x32_bf16 v[86:89], v[156:159], v[202:205], v[86:89]
	v_mfma_f32_16x16x32_bf16 v[78:81], v[148:151], v[224:227], v[78:81]
	v_mfma_f32_16x16x32_bf16 v[70:73], v[156:159], v[224:227], v[70:73]
	s_setprio 0
	s_setprio 1
	v_mfma_f32_16x16x32_bf16 v[122:125], v[160:163], v[176:179], v[122:125]
	v_mfma_f32_16x16x32_bf16 v[114:117], v[168:171], v[176:179], v[114:117]
	v_mfma_f32_16x16x32_bf16 v[106:109], v[160:163], v[184:187], v[106:109]
	v_mfma_f32_16x16x32_bf16 v[98:101], v[168:171], v[184:187], v[98:101]
	v_mfma_f32_16x16x32_bf16 v[90:93], v[160:163], v[192:195], v[90:93]
	v_mfma_f32_16x16x32_bf16 v[82:85], v[168:171], v[192:195], v[82:85]
	v_mfma_f32_16x16x32_bf16 v[74:77], v[160:163], v[214:217], v[74:77]
	v_mfma_f32_16x16x32_bf16 v[66:69], v[168:171], v[214:217], v[66:69]
	v_mfma_f32_16x16x32_bf16 v[122:125], v[164:167], v[180:183], v[122:125]
	v_mfma_f32_16x16x32_bf16 v[114:117], v[172:175], v[180:183], v[114:117]
	v_mfma_f32_16x16x32_bf16 v[106:109], v[164:167], v[188:191], v[106:109]
	v_mfma_f32_16x16x32_bf16 v[98:101], v[172:175], v[188:191], v[98:101]
	v_mfma_f32_16x16x32_bf16 v[90:93], v[164:167], v[202:205], v[90:93]
	v_mfma_f32_16x16x32_bf16 v[82:85], v[172:175], v[202:205], v[82:85]
	v_mfma_f32_16x16x32_bf16 v[74:77], v[164:167], v[224:227], v[74:77]
	v_mfma_f32_16x16x32_bf16 v[66:69], v[172:175], v[224:227], v[66:69]
	s_setprio 0
	s_barrier
	s_add_i32 s54, s54, s37
	v_lshl_add_u64 v[196:197], s[24:25], 0, v[0:1]
	s_mov_b32 m0, s54
	ds_read_b128 v[176:179], v143 offset:16384
	ds_read_b128 v[180:183], v143 offset:17408
	ds_read_b128 v[184:187], v143 offset:18432
	ds_read_b128 v[188:191], v143 offset:19456
	ds_read_b128 v[192:195], v143 offset:20480
	ds_read_b128 v[202:205], v143 offset:21504
	ds_read_b128 v[214:217], v143 offset:22528
	ds_read_b128 v[224:227], v143 offset:23552
	global_load_lds_dwordx4 v[196:197], off
	s_add_i32 m0, s54, 0x2000
	s_add_u32 s54, s24, 0x40000
	v_lshl_add_u64 v[198:199], s[24:25], 0, v[130:131]
	s_addc_u32 s55, s25, 0
	s_add_i32 s56, s56, s37
	global_load_lds_dwordx4 v[198:199], off
	v_lshl_add_u64 v[200:201], s[54:55], 0, v[0:1]
	s_mov_b32 m0, s56
	v_lshl_add_u64 v[206:207], s[26:27], 0, v[132:133]
	global_load_lds_dwordx4 v[200:201], off
	v_lshl_add_u64 v[200:201], s[54:55], 0, v[130:131]
	s_add_i32 m0, s56, 0x2000
	s_nop 0
	global_load_lds_dwordx4 v[200:201], off
	v_lshl_add_u64 v[200:201], s[26:27], 0, v[134:135]
	s_mov_b32 m0, s38
	s_nop 0
	global_load_lds_dwordx4 v[200:201], off
	s_mov_b32 m0, s39
	s_nop 0
	global_load_lds_dwordx4 v[206:207], off
	s_cmp_lg_u32 s53, 12
	s_cbranch_scc1 .Lp3w_nlA
	s_lshl_b32 s56, s47, 8
	s_add_i32 s56, s56, s42
	v_and_b32_e32 v228, 15, v212
	v_lshrrev_b32_e32 v229, 4, v212
	v_or_b32_e32 v228, s56, v228
	v_lshlrev_b32_e32 v228, 6, v228
	v_lshl_add_u32 v230, v229, 4, v228
	v_mov_b32_e32 v231, 0
	v_lshl_add_u64 v[250:251], s[6:7], 0, v[230:231]
	v_mov_b32_e32 v230, 0x2000
	v_lshl_add_u64 v[248:249], v[250:251], 0, v[230:231]
	global_load_dwordx4 v[228:231], v[250:251], off
	global_load_dwordx4 v[232:235], v[250:251], off offset:1024
	global_load_dwordx4 v[236:239], v[250:251], off offset:2048
	global_load_dwordx4 v[240:243], v[250:251], off offset:3072
	global_load_dwordx4 v[244:247], v[248:249], off
	s_nop 0
	global_load_dwordx4 v[248:251], v[248:249], off offset:1024
	s_waitcnt vmcnt(14)
	s_branch .Lp3w_jA
.Lp3w_nlA:
	s_waitcnt vmcnt(8)
.Lp3w_jA:
	s_waitcnt lgkmcnt(0)
	s_barrier
	s_setprio 1
	s_waitcnt lgkmcnt(0)
	v_mfma_f32_16x16x32_bf16 v[62:65], v[144:147], v[176:179], v[62:65]
	v_mfma_f32_16x16x32_bf16 v[54:57], v[152:155], v[176:179], v[54:57]
	v_mfma_f32_16x16x32_bf16 v[46:49], v[144:147], v[184:187], v[46:49]
	v_mfma_f32_16x16x32_bf16 v[38:41], v[152:155], v[184:187], v[38:41]
	v_mfma_f32_16x16x32_bf16 v[30:33], v[144:147], v[192:195], v[30:33]
	v_mfma_f32_16x16x32_bf16 v[22:25], v[152:155], v[192:195], v[22:25]
	v_mfma_f32_16x16x32_bf16 v[14:17], v[144:147], v[214:217], v[14:17]
	v_mfma_f32_16x16x32_bf16 v[6:9], v[152:155], v[214:217], v[6:9]
	v_mfma_f32_16x16x32_bf16 v[62:65], v[148:151], v[180:183], v[62:65]
	v_mfma_f32_16x16x32_bf16 v[54:57], v[156:159], v[180:183], v[54:57]
	v_mfma_f32_16x16x32_bf16 v[46:49], v[148:151], v[188:191], v[46:49]
	v_mfma_f32_16x16x32_bf16 v[38:41], v[156:159], v[188:191], v[38:41]
	v_mfma_f32_16x16x32_bf16 v[30:33], v[148:151], v[202:205], v[30:33]
	v_mfma_f32_16x16x32_bf16 v[22:25], v[156:159], v[202:205], v[22:25]
	v_mfma_f32_16x16x32_bf16 v[14:17], v[148:151], v[224:227], v[14:17]
	v_mfma_f32_16x16x32_bf16 v[6:9], v[156:159], v[224:227], v[6:9]
	s_setprio 0
	s_setprio 1
	v_mfma_f32_16x16x32_bf16 v[58:61], v[160:163], v[176:179], v[58:61]
	v_mfma_f32_16x16x32_bf16 v[50:53], v[168:171], v[176:179], v[50:53]
	v_mfma_f32_16x16x32_bf16 v[42:45], v[160:163], v[184:187], v[42:45]
	v_mfma_f32_16x16x32_bf16 v[34:37], v[168:171], v[184:187], v[34:37]
	v_mfma_f32_16x16x32_bf16 v[26:29], v[160:163], v[192:195], v[26:29]
	v_mfma_f32_16x16x32_bf16 v[18:21], v[168:171], v[192:195], v[18:21]
	v_mfma_f32_16x16x32_bf16 v[10:13], v[160:163], v[214:217], v[10:13]
	v_mfma_f32_16x16x32_bf16 v[2:5], v[168:171], v[214:217], v[2:5]
	v_mfma_f32_16x16x32_bf16 v[58:61], v[164:167], v[180:183], v[58:61]
	v_mfma_f32_16x16x32_bf16 v[50:53], v[172:175], v[180:183], v[50:53]
	v_mfma_f32_16x16x32_bf16 v[42:45], v[164:167], v[188:191], v[42:45]
	v_mfma_f32_16x16x32_bf16 v[34:37], v[172:175], v[188:191], v[34:37]
	v_mfma_f32_16x16x32_bf16 v[26:29], v[164:167], v[202:205], v[26:29]
	v_mfma_f32_16x16x32_bf16 v[18:21], v[172:175], v[202:205], v[18:21]
	v_mfma_f32_16x16x32_bf16 v[10:13], v[164:167], v[224:227], v[10:13]
	v_mfma_f32_16x16x32_bf16 v[2:5], v[172:175], v[224:227], v[2:5]
	s_setprio 0
	s_barrier
	s_add_i32 s54, 0, 0x18000
	v_add_u32_e32 v140, s54, v141
	s_add_i32 s55, 0, 0x1c000
	ds_read_b128 v[144:147], v140
	ds_read_b128 v[148:151], v140 offset:1024
	ds_read_b128 v[152:155], v140 offset:2048
	ds_read_b128 v[156:159], v140 offset:3072
	v_add_u32_e32 v140, s55, v141
	ds_read_b128 v[160:163], v140
	ds_read_b128 v[164:167], v140 offset:1024
	ds_read_b128 v[168:171], v140 offset:2048
	ds_read_b128 v[172:175], v140 offset:3072
	s_add_u32 s26, s26, 0x40000
	s_addc_u32 s27, s27, 0
	s_mov_b32 m0, s40
	v_lshl_add_u64 v[210:211], s[26:27], 0, v[134:135]
	ds_read_b128 v[176:179], v143 offset:32768
	ds_read_b128 v[180:183], v143 offset:33792
	ds_read_b128 v[184:187], v143 offset:34816
	ds_read_b128 v[188:191], v143 offset:35840
	ds_read_b128 v[192:195], v143 offset:36864
	ds_read_b128 v[202:205], v143 offset:37888
	ds_read_b128 v[214:217], v143 offset:38912
	ds_read_b128 v[224:227], v143 offset:39936
	global_load_lds_dwordx4 v[210:211], off
	v_lshl_add_u64 v[210:211], s[26:27], 0, v[132:133]
	s_mov_b32 m0, s41
	s_nop 0
	global_load_lds_dwordx4 v[210:211], off
	s_cmp_lg_u32 s53, 12
	s_cbranch_scc1 .Lp3w_nlB
	s_waitcnt vmcnt(14)
	s_branch .Lp3w_jB

.Lp3w_jB:
	s_waitcnt lgkmcnt(0)
	s_barrier
	s_setprio 1
	s_waitcnt lgkmcnt(0)
	v_mfma_f32_16x16x32_bf16 v[126:129], v[144:147], v[176:179], v[126:129]
	v_mfma_f32_16x16x32_bf16 v[118:121], v[152:155], v[176:179], v[118:121]
	v_mfma_f32_16x16x32_bf16 v[110:113], v[144:147], v[184:187], v[110:113]
	v_mfma_f32_16x16x32_bf16 v[102:105], v[152:155], v[184:187], v[102:105]
	v_mfma_f32_16x16x32_bf16 v[94:97], v[144:147], v[192:195], v[94:97]
	v_mfma_f32_16x16x32_bf16 v[86:89], v[152:155], v[192:195], v[86:89]
	v_mfma_f32_16x16x32_bf16 v[78:81], v[144:147], v[214:217], v[78:81]
	v_mfma_f32_16x16x32_bf16 v[70:73], v[152:155], v[214:217], v[70:73]
	v_mfma_f32_16x16x32_bf16 v[126:129], v[148:151], v[180:183], v[126:129]
	v_mfma_f32_16x16x32_bf16 v[118:121], v[156:159], v[180:183], v[118:121]
	v_mfma_f32_16x16x32_bf16 v[110:113], v[148:151], v[188:191], v[110:113]
	v_mfma_f32_16x16x32_bf16 v[102:105], v[156:159], v[188:191], v[102:105]
	v_mfma_f32_16x16x32_bf16 v[94:97], v[148:151], v[202:205], v[94:97]
	v_mfma_f32_16x16x32_bf16 v[86:89], v[156:159], v[202:205], v[86:89]
	v_mfma_f32_16x16x32_bf16 v[78:81], v[148:151], v[224:227], v[78:81]
	v_mfma_f32_16x16x32_bf16 v[70:73], v[156:159], v[224:227], v[70:73]
	s_setprio 0
	s_setprio 1
	v_mfma_f32_16x16x32_bf16 v[122:125], v[160:163], v[176:179], v[122:125]
	v_mfma_f32_16x16x32_bf16 v[114:117], v[168:171], v[176:179], v[114:117]
	v_mfma_f32_16x16x32_bf16 v[106:109], v[160:163], v[184:187], v[106:109]
	v_mfma_f32_16x16x32_bf16 v[98:101], v[168:171], v[184:187], v[98:101]
	v_mfma_f32_16x16x32_bf16 v[90:93], v[160:163], v[192:195], v[90:93]
	v_mfma_f32_16x16x32_bf16 v[82:85], v[168:171], v[192:195], v[82:85]
	v_mfma_f32_16x16x32_bf16 v[74:77], v[160:163], v[214:217], v[74:77]
	v_mfma_f32_16x16x32_bf16 v[66:69], v[168:171], v[214:217], v[66:69]
	v_mfma_f32_16x16x32_bf16 v[122:125], v[164:167], v[180:183], v[122:125]
	v_mfma_f32_16x16x32_bf16 v[114:117], v[172:175], v[180:183], v[114:117]
	v_mfma_f32_16x16x32_bf16 v[106:109], v[164:167], v[188:191], v[106:109]
	v_mfma_f32_16x16x32_bf16 v[98:101], v[172:175], v[188:191], v[98:101]
	v_mfma_f32_16x16x32_bf16 v[90:93], v[164:167], v[202:205], v[90:93]
	v_mfma_f32_16x16x32_bf16 v[82:85], v[172:175], v[202:205], v[82:85]
	v_mfma_f32_16x16x32_bf16 v[74:77], v[164:167], v[224:227], v[74:77]
	v_mfma_f32_16x16x32_bf16 v[66:69], v[172:175], v[224:227], v[66:69]
	s_setprio 0
	s_barrier
	s_add_i32 s26, s54, s37
	v_lshl_add_u64 v[196:197], v[196:197], 0, s[94:95]
	s_mov_b32 m0, s26
	ds_read_b128 v[176:179], v143 offset:49152
	ds_read_b128 v[180:183], v143 offset:50176
	ds_read_b128 v[184:187], v143 offset:51200
	ds_read_b128 v[188:191], v143 offset:52224
	ds_read_b128 v[192:195], v143 offset:53248
	ds_read_b128 v[202:205], v143 offset:54272
	ds_read_b128 v[214:217], v143 offset:55296
	ds_read_b128 v[224:227], v143 offset:56320
	global_load_lds_dwordx4 v[196:197], off
	s_add_i32 m0, s26, 0x2000
	s_add_u32 s24, s24, 0x40080
	v_lshl_add_u64 v[196:197], v[198:199], 0, s[94:95]
	s_addc_u32 s25, s25, 0
	s_add_i32 s26, s55, s37
	global_load_lds_dwordx4 v[196:197], off
	v_lshl_add_u64 v[196:197], s[24:25], 0, v[0:1]
	s_mov_b32 m0, s26
	s_nop 0
	global_load_lds_dwordx4 v[196:197], off
	v_lshl_add_u64 v[196:197], s[24:25], 0, v[130:131]
	s_add_i32 m0, s26, 0x2000
	s_nop 0
	global_load_lds_dwordx4 v[196:197], off
	v_lshl_add_u64 v[196:197], v[200:201], 0, s[94:95]
	s_mov_b32 m0, s44
	s_nop 0
	global_load_lds_dwordx4 v[196:197], off
	v_lshl_add_u64 v[196:197], v[206:207], 0, s[94:95]
	s_mov_b32 m0, s45
	s_nop 0
	global_load_lds_dwordx4 v[196:197], off
	s_cmp_lg_u32 s53, 12
	s_cbranch_scc1 .Lp3w_nlC
	s_lshl_b32 s56, s47, 8
	s_add_i32 s56, s56, s42
	v_and_b32_e32 v196, 15, v212
	v_lshrrev_b32_e32 v197, 4, v212
	v_or_b32_e32 v196, s56, v196
	v_lshlrev_b32_e32 v196, 6, v196
	v_lshl_add_u32 v196, v197, 4, v196
	v_add_u32_e32 v196, 0x2800, v196
	v_mov_b32_e32 v197, 0
	v_lshl_add_u64 v[210:211], s[6:7], 0, v[196:197]
	global_load_dwordx4 v[196:199], v[210:211], off
	global_load_dwordx2 v[200:201], v[210:211], off offset:1024
	global_load_dwordx2 v[206:207], v[210:211], off offset:1032
	s_waitcnt vmcnt(17)
	s_branch .Lp3w_jC

.Lp3w_jC:
	s_waitcnt lgkmcnt(0)
	s_barrier
	s_setprio 1
	s_waitcnt lgkmcnt(0)
	v_mfma_f32_16x16x32_bf16 v[62:65], v[144:147], v[176:179], v[62:65]
	v_mfma_f32_16x16x32_bf16 v[54:57], v[152:155], v[176:179], v[54:57]
	v_mfma_f32_16x16x32_bf16 v[46:49], v[144:147], v[184:187], v[46:49]
	v_mfma_f32_16x16x32_bf16 v[38:41], v[152:155], v[184:187], v[38:41]
	v_mfma_f32_16x16x32_bf16 v[30:33], v[144:147], v[192:195], v[30:33]
	v_mfma_f32_16x16x32_bf16 v[22:25], v[152:155], v[192:195], v[22:25]
	v_mfma_f32_16x16x32_bf16 v[14:17], v[144:147], v[214:217], v[14:17]
	v_mfma_f32_16x16x32_bf16 v[6:9], v[152:155], v[214:217], v[6:9]
	v_mfma_f32_16x16x32_bf16 v[62:65], v[148:151], v[180:183], v[62:65]
	v_mfma_f32_16x16x32_bf16 v[54:57], v[156:159], v[180:183], v[54:57]
	v_mfma_f32_16x16x32_bf16 v[46:49], v[148:151], v[188:191], v[46:49]
	v_mfma_f32_16x16x32_bf16 v[38:41], v[156:159], v[188:191], v[38:41]
	v_mfma_f32_16x16x32_bf16 v[30:33], v[148:151], v[202:205], v[30:33]
	v_mfma_f32_16x16x32_bf16 v[22:25], v[156:159], v[202:205], v[22:25]
	v_mfma_f32_16x16x32_bf16 v[14:17], v[148:151], v[224:227], v[14:17]
	v_mfma_f32_16x16x32_bf16 v[6:9], v[156:159], v[224:227], v[6:9]
	s_setprio 0
	s_setprio 1
	v_mfma_f32_16x16x32_bf16 v[58:61], v[160:163], v[176:179], v[58:61]
	v_mfma_f32_16x16x32_bf16 v[50:53], v[168:171], v[176:179], v[50:53]
	v_mfma_f32_16x16x32_bf16 v[42:45], v[160:163], v[184:187], v[42:45]
	v_mfma_f32_16x16x32_bf16 v[34:37], v[168:171], v[184:187], v[34:37]
	v_mfma_f32_16x16x32_bf16 v[26:29], v[160:163], v[192:195], v[26:29]
	v_mfma_f32_16x16x32_bf16 v[18:21], v[168:171], v[192:195], v[18:21]
	v_mfma_f32_16x16x32_bf16 v[10:13], v[160:163], v[214:217], v[10:13]
	v_mfma_f32_16x16x32_bf16 v[2:5], v[168:171], v[214:217], v[2:5]
	v_mfma_f32_16x16x32_bf16 v[58:61], v[164:167], v[180:183], v[58:61]
	v_mfma_f32_16x16x32_bf16 v[50:53], v[172:175], v[180:183], v[50:53]
	v_mfma_f32_16x16x32_bf16 v[42:45], v[164:167], v[188:191], v[42:45]
	v_mfma_f32_16x16x32_bf16 v[34:37], v[172:175], v[188:191], v[34:37]
	v_mfma_f32_16x16x32_bf16 v[26:29], v[164:167], v[202:205], v[26:29]
	v_mfma_f32_16x16x32_bf16 v[18:21], v[172:175], v[202:205], v[18:21]
	v_mfma_f32_16x16x32_bf16 v[10:13], v[164:167], v[224:227], v[10:13]
	v_mfma_f32_16x16x32_bf16 v[2:5], v[172:175], v[224:227], v[2:5]
	s_setprio 0
	s_barrier
	s_add_i32 s53, s53, 2
	s_add_u32 s22, s22, 0x100
	s_addc_u32 s23, s23, 0
	s_add_u32 s51, s51, 0x100
	s_addc_u32 s52, s52, 0
	s_cmp_gt_u32 s53, 13
	s_cbranch_scc0 .LBB0_1083
	v_mov_b32_e32 v140, v212
	s_lshl_b32 s13, s48, 7
	v_and_b32_e32 v153, 15, v140
	v_ashrrev_i32_e32 v140, 4, v140
	s_or_b32 s13, s13, s43
	v_lshl_add_u32 v152, v140, 3, s13
	s_lshl_b32 s13, s47, 8
	s_movk_i32 s15, 0x2000
	v_readlane_b32 s26, v252, 55
	s_and_b64 vcc, exec, s[10:11]
	s_cbranch_vccz .LBB0_1086
	s_barrier
.LBB0_1086:
	s_andn2_b64 vcc, exec, s[16:17]
	s_waitcnt vmcnt(11)
	v_add_f32_e32 v140, v228, v229
	v_add_f32_e32 v142, v230, v231
	v_add_f32_e32 v140, v140, v142
	v_add_f32_e32 v142, v232, v233
	v_add_f32_e32 v144, v234, v235
	v_add_f32_e32 v142, v142, v144
	v_add_f32_e32 v144, v236, v237
	v_add_f32_e32 v145, v238, v239
	v_add_f32_e32 v144, v144, v145
	v_add_f32_e32 v145, v240, v241
	v_add_f32_e32 v146, v242, v243
	v_add_f32_e32 v145, v145, v146
	v_add_f32_e32 v146, v244, v245
	v_add_f32_e32 v147, v246, v247
	v_add_f32_e32 v146, v146, v147
	v_add_f32_e32 v147, v248, v249
	v_add_f32_e32 v148, v250, v251
	v_add_f32_e32 v147, v147, v148
	v_mov_b32_e32 v150, v140
	s_nop 1
	v_permlane16_swap_b32_e32 v140, v150
	v_add_f32_e32 v140, v140, v150
	v_mov_b32_e32 v150, v142
	s_nop 1
	v_permlane16_swap_b32_e32 v142, v150
	v_add_f32_e32 v142, v142, v150
	v_mov_b32_e32 v150, v144
	s_nop 1
	v_permlane16_swap_b32_e32 v144, v150
	v_add_f32_e32 v144, v144, v150
	v_mov_b32_e32 v150, v145
	s_nop 1
	v_permlane16_swap_b32_e32 v145, v150
	v_add_f32_e32 v145, v145, v150
	v_mov_b32_e32 v150, v146
	s_nop 1
	v_permlane16_swap_b32_e32 v146, v150
	v_add_f32_e32 v146, v146, v150
	v_mov_b32_e32 v150, v147
	s_nop 1
	v_permlane16_swap_b32_e32 v147, v150
	v_add_f32_e32 v147, v147, v150
	v_mov_b32_e32 v150, v140
	s_nop 1
	v_permlane32_swap_b32_e32 v140, v150
	v_add_f32_e32 v140, v140, v150
	v_mov_b32_e32 v150, v142
	s_nop 1
	v_permlane32_swap_b32_e32 v142, v150
	v_add_f32_e32 v142, v142, v150
	v_mov_b32_e32 v150, v144
	s_nop 1
	v_permlane32_swap_b32_e32 v144, v150
	v_add_f32_e32 v144, v144, v150
	v_mov_b32_e32 v150, v145
	s_nop 1
	v_permlane32_swap_b32_e32 v145, v150
	v_add_f32_e32 v145, v145, v150
	v_mov_b32_e32 v150, v146
	s_nop 1
	v_permlane32_swap_b32_e32 v146, v150
	v_add_f32_e32 v146, v146, v150
	v_mov_b32_e32 v150, v147
	s_nop 1
	v_permlane32_swap_b32_e32 v147, v150
	v_fmamk_f32 v140, v140, 0x3a800000, v213
	v_add_f32_e32 v147, v147, v150
	v_rsq_f32_e32 v156, v140
	s_nop 0
	v_fmamk_f32 v140, v142, 0x3a800000, v213
	v_rsq_f32_e32 v154, v140
	v_fmamk_f32 v140, v144, 0x3a800000, v213
	v_rsq_f32_e32 v150, v140
	v_fmamk_f32 v140, v145, 0x3a800000, v213
	v_rsq_f32_e32 v148, v140
	v_fmamk_f32 v140, v146, 0x3a800000, v213
	v_pk_mul_f32 v[126:127], v[126:127], v[156:157] op_sel_hi:[1,0]
	v_rsq_f32_e32 v146, v140
	v_fmamk_f32 v140, v147, 0x3a800000, v213
	v_mul_f32_e32 v147, 0xbfb8aa3b, v126
	v_exp_f32_e32 v147, v147
	v_pk_mul_f32 v[122:123], v[122:123], v[156:157] op_sel_hi:[1,0]
	v_pk_mul_f32 v[124:125], v[124:125], v[156:157] op_sel_hi:[1,0]
	v_pk_mul_f32 v[118:119], v[118:119], v[156:157] op_sel_hi:[1,0]
	v_add_f32_e32 v147, 1.0, v147
	v_rcp_f32_e32 v158, v147
	v_mul_f32_e32 v147, 0xbfb8aa3b, v127
	v_exp_f32_e32 v147, v147
	v_pk_mul_f32 v[114:115], v[114:115], v[156:157] op_sel_hi:[1,0]
	v_pk_mul_f32 v[116:117], v[116:117], v[156:157] op_sel_hi:[1,0]
	v_pk_mul_f32 v[110:111], v[110:111], v[154:155] op_sel_hi:[1,0]
	v_add_f32_e32 v147, 1.0, v147
	v_rcp_f32_e32 v159, v147
	v_or_b32_e32 v145, s42, v153
	v_ashrrev_i32_e32 v153, 31, v152
	v_pk_mul_f32 v[106:107], v[106:107], v[154:155] op_sel_hi:[1,0]
	v_pk_mul_f32 v[126:127], v[126:127], v[158:159]
	v_pk_mul_f32 v[108:109], v[108:109], v[154:155] op_sel_hi:[1,0]
	v_pk_mul_f32 v[122:123], v[122:123], v[126:127]
	v_pk_mul_f32 v[126:127], v[128:129], v[156:157] op_sel_hi:[1,0]
	v_cvt_pk_bf16_f32 v122, v122, v123
	v_mul_f32_e32 v128, 0xbfb8aa3b, v126
	v_mul_f32_e32 v129, 0xbfb8aa3b, v127
	v_exp_f32_e32 v128, v128
	v_exp_f32_e32 v129, v129
	v_pk_mul_f32 v[102:103], v[102:103], v[154:155] op_sel_hi:[1,0]
	v_pk_mul_f32 v[98:99], v[98:99], v[154:155] op_sel_hi:[1,0]
	v_add_f32_e32 v128, 1.0, v128
	v_add_f32_e32 v129, 1.0, v129
	v_rcp_f32_e32 v128, v128
	v_rcp_f32_e32 v129, v129
	v_pk_mul_f32 v[100:101], v[100:101], v[154:155] op_sel_hi:[1,0]
	v_pk_mul_f32 v[94:95], v[94:95], v[150:151] op_sel_hi:[1,0]
	v_pk_mul_f32 v[90:91], v[90:91], v[150:151] op_sel_hi:[1,0]
	v_pk_mul_f32 v[126:127], v[126:127], v[128:129]
	v_pk_mul_f32 v[92:93], v[92:93], v[150:151] op_sel_hi:[1,0]
	v_pk_mul_f32 v[124:125], v[124:125], v[126:127]
	v_pk_mul_f32 v[86:87], v[86:87], v[150:151] op_sel_hi:[1,0]
	v_cvt_pk_bf16_f32 v123, v124, v125
	v_mul_f32_e32 v124, 0xbfb8aa3b, v118
	v_mul_f32_e32 v125, 0xbfb8aa3b, v119
	v_exp_f32_e32 v124, v124
	v_exp_f32_e32 v125, v125
	v_pk_mul_f32 v[82:83], v[82:83], v[150:151] op_sel_hi:[1,0]
	v_pk_mul_f32 v[84:85], v[84:85], v[150:151] op_sel_hi:[1,0]
	v_add_f32_e32 v124, 1.0, v124
	v_add_f32_e32 v125, 1.0, v125
	v_rcp_f32_e32 v124, v124
	v_rcp_f32_e32 v125, v125
	v_pk_mul_f32 v[78:79], v[78:79], v[148:149] op_sel_hi:[1,0]
	v_pk_mul_f32 v[74:75], v[74:75], v[148:149] op_sel_hi:[1,0]
	v_pk_mul_f32 v[76:77], v[76:77], v[148:149] op_sel_hi:[1,0]
	v_pk_mul_f32 v[118:119], v[118:119], v[124:125]
	v_pk_mul_f32 v[70:71], v[70:71], v[148:149] op_sel_hi:[1,0]
	v_pk_mul_f32 v[114:115], v[114:115], v[118:119]
	v_pk_mul_f32 v[118:119], v[120:121], v[156:157] op_sel_hi:[1,0]
	v_cvt_pk_bf16_f32 v124, v114, v115
	v_mul_f32_e32 v120, 0xbfb8aa3b, v118
	v_mul_f32_e32 v121, 0xbfb8aa3b, v119
	v_exp_f32_e32 v120, v120
	v_exp_f32_e32 v121, v121
	v_mov_b64_e32 v[114:115], s[8:9]
	v_pk_mul_f32 v[66:67], v[66:67], v[148:149] op_sel_hi:[1,0]
	v_add_f32_e32 v120, 1.0, v120
	v_add_f32_e32 v121, 1.0, v121
	v_rcp_f32_e32 v120, v120
	v_rcp_f32_e32 v121, v121
	v_pk_mul_f32 v[68:69], v[68:69], v[148:149] op_sel_hi:[1,0]
	v_pk_mul_f32 v[62:63], v[62:63], v[146:147] op_sel_hi:[1,0]
	v_pk_mul_f32 v[58:59], v[58:59], v[146:147] op_sel_hi:[1,0]
	v_pk_mul_f32 v[118:119], v[118:119], v[120:121]
	v_pk_mul_f32 v[60:61], v[60:61], v[146:147] op_sel_hi:[1,0]
	v_pk_mul_f32 v[116:117], v[116:117], v[118:119]
	v_mul_f32_e32 v119, 0xbfb8aa3b, v110
	v_exp_f32_e32 v119, v119
	v_add_u32_e32 v118, s13, v145
	v_cvt_pk_bf16_f32 v125, v116, v117
	v_mad_i64_i32 v[120:121], s[22:23], v118, s66, v[114:115]
	v_lshlrev_b64 v[116:117], 1, v[152:153]
	v_lshl_add_u64 v[120:121], v[120:121], 0, v[116:117]
	v_add_f32_e32 v119, 1.0, v119
	global_store_dwordx4 v[120:121], v[122:125], off
	v_rcp_f32_e32 v120, v119
	v_mul_f32_e32 v119, 0xbfb8aa3b, v111
	v_exp_f32_e32 v119, v119
	v_pk_mul_f32 v[54:55], v[54:55], v[146:147] op_sel_hi:[1,0]
	v_pk_mul_f32 v[50:51], v[50:51], v[146:147] op_sel_hi:[1,0]
	v_rsq_f32_e32 v144, v140
	v_add_f32_e32 v119, 1.0, v119
	v_rcp_f32_e32 v121, v119
	v_pk_mul_f32 v[52:53], v[52:53], v[146:147] op_sel_hi:[1,0]
	v_pk_mul_f32 v[46:47], v[46:47], v[144:145] op_sel_hi:[1,0]
	v_pk_mul_f32 v[42:43], v[42:43], v[144:145] op_sel_hi:[1,0]
	v_pk_mul_f32 v[110:111], v[110:111], v[120:121]
	v_pk_mul_f32 v[44:45], v[44:45], v[144:145] op_sel_hi:[1,0]
	v_pk_mul_f32 v[106:107], v[106:107], v[110:111]
	v_pk_mul_f32 v[110:111], v[112:113], v[154:155] op_sel_hi:[1,0]
	v_cvt_pk_bf16_f32 v106, v106, v107
	v_mul_f32_e32 v112, 0xbfb8aa3b, v110
	v_mul_f32_e32 v113, 0xbfb8aa3b, v111
	v_exp_f32_e32 v112, v112
	v_exp_f32_e32 v113, v113
	v_pk_mul_f32 v[38:39], v[38:39], v[144:145] op_sel_hi:[1,0]
	v_pk_mul_f32 v[34:35], v[34:35], v[144:145] op_sel_hi:[1,0]
	v_add_f32_e32 v112, 1.0, v112
	v_add_f32_e32 v113, 1.0, v113
	v_rcp_f32_e32 v112, v112
	v_rcp_f32_e32 v113, v113
	v_pk_mul_f32 v[36:37], v[36:37], v[144:145] op_sel_hi:[1,0]
	v_pk_mul_f32 v[110:111], v[110:111], v[112:113]
	v_pk_mul_f32 v[108:109], v[108:109], v[110:111]
	v_cvt_pk_bf16_f32 v107, v108, v109
	v_mul_f32_e32 v108, 0xbfb8aa3b, v102
	v_mul_f32_e32 v109, 0xbfb8aa3b, v103
	v_exp_f32_e32 v108, v108
	v_exp_f32_e32 v109, v109
	v_add_f32_e32 v108, 1.0, v108
	v_add_f32_e32 v109, 1.0, v109
	v_rcp_f32_e32 v108, v108
	v_rcp_f32_e32 v109, v109
	s_nop 0
	v_pk_mul_f32 v[102:103], v[102:103], v[108:109]
	v_pk_mul_f32 v[98:99], v[98:99], v[102:103]
	v_pk_mul_f32 v[102:103], v[104:105], v[154:155] op_sel_hi:[1,0]
	v_cvt_pk_bf16_f32 v108, v98, v99
	v_mul_f32_e32 v104, 0xbfb8aa3b, v102
	v_mul_f32_e32 v105, 0xbfb8aa3b, v103
	v_exp_f32_e32 v104, v104
	v_exp_f32_e32 v105, v105
	v_or_b32_e32 v98, 16, v118
	v_mad_i64_i32 v[98:99], s[22:23], v98, s66, v[114:115]
	v_add_f32_e32 v104, 1.0, v104
	v_add_f32_e32 v105, 1.0, v105
	v_rcp_f32_e32 v104, v104
	v_rcp_f32_e32 v105, v105
	v_lshl_add_u64 v[98:99], v[98:99], 0, v[116:117]
	v_pk_mul_f32 v[102:103], v[102:103], v[104:105]
	v_pk_mul_f32 v[100:101], v[100:101], v[102:103]
	v_cvt_pk_bf16_f32 v109, v100, v101
	global_store_dwordx4 v[98:99], v[106:109], off
	v_mul_f32_e32 v98, 0xbfb8aa3b, v94
	v_mul_f32_e32 v99, 0xbfb8aa3b, v95
	v_exp_f32_e32 v98, v98
	v_exp_f32_e32 v99, v99
	v_add_f32_e32 v98, 1.0, v98
	v_add_f32_e32 v99, 1.0, v99
	v_rcp_f32_e32 v98, v98
	v_rcp_f32_e32 v99, v99
	s_nop 0
	v_pk_mul_f32 v[94:95], v[94:95], v[98:99]
	s_nop 0
	v_pk_mul_f32 v[90:91], v[90:91], v[94:95]
	v_pk_mul_f32 v[94:95], v[96:97], v[150:151] op_sel_hi:[1,0]
	v_cvt_pk_bf16_f32 v90, v90, v91
	v_mul_f32_e32 v96, 0xbfb8aa3b, v94
	v_mul_f32_e32 v97, 0xbfb8aa3b, v95
	v_exp_f32_e32 v96, v96
	v_exp_f32_e32 v97, v97
	v_add_f32_e32 v96, 1.0, v96
	v_add_f32_e32 v97, 1.0, v97
	v_rcp_f32_e32 v96, v96
	v_rcp_f32_e32 v97, v97
	s_nop 0
	v_pk_mul_f32 v[94:95], v[94:95], v[96:97]
	s_nop 0
	v_pk_mul_f32 v[92:93], v[92:93], v[94:95]
	s_nop 0
	v_cvt_pk_bf16_f32 v91, v92, v93
	v_mul_f32_e32 v92, 0xbfb8aa3b, v86
	v_mul_f32_e32 v93, 0xbfb8aa3b, v87
	v_exp_f32_e32 v92, v92
	v_exp_f32_e32 v93, v93
	v_add_f32_e32 v92, 1.0, v92
	v_add_f32_e32 v93, 1.0, v93
	v_rcp_f32_e32 v92, v92
	v_rcp_f32_e32 v93, v93
	s_nop 0
	v_pk_mul_f32 v[86:87], v[86:87], v[92:93]
	s_nop 0
	v_pk_mul_f32 v[82:83], v[82:83], v[86:87]
	v_pk_mul_f32 v[86:87], v[88:89], v[150:151] op_sel_hi:[1,0]
	v_cvt_pk_bf16_f32 v92, v82, v83
	v_mul_f32_e32 v88, 0xbfb8aa3b, v86
	v_mul_f32_e32 v89, 0xbfb8aa3b, v87
	v_exp_f32_e32 v88, v88
	v_exp_f32_e32 v89, v89
	v_or_b32_e32 v82, 32, v118
	v_mad_i64_i32 v[82:83], s[22:23], v82, s66, v[114:115]
	v_add_f32_e32 v88, 1.0, v88
	v_add_f32_e32 v89, 1.0, v89
	v_rcp_f32_e32 v88, v88
	v_rcp_f32_e32 v89, v89
	v_lshl_add_u64 v[82:83], v[82:83], 0, v[116:117]
	v_pk_mul_f32 v[86:87], v[86:87], v[88:89]
	s_nop 0
	v_pk_mul_f32 v[84:85], v[84:85], v[86:87]
	s_nop 0
	v_cvt_pk_bf16_f32 v93, v84, v85
	global_store_dwordx4 v[82:83], v[90:93], off
	v_mul_f32_e32 v82, 0xbfb8aa3b, v78
	v_mul_f32_e32 v83, 0xbfb8aa3b, v79
	v_exp_f32_e32 v82, v82
	v_exp_f32_e32 v83, v83
	v_add_f32_e32 v82, 1.0, v82
	v_add_f32_e32 v83, 1.0, v83
	v_rcp_f32_e32 v82, v82
	v_rcp_f32_e32 v83, v83
	s_nop 0
	v_pk_mul_f32 v[78:79], v[78:79], v[82:83]
	s_nop 0
	v_pk_mul_f32 v[74:75], v[74:75], v[78:79]
	v_pk_mul_f32 v[78:79], v[80:81], v[148:149] op_sel_hi:[1,0]
	v_cvt_pk_bf16_f32 v74, v74, v75
	v_mul_f32_e32 v80, 0xbfb8aa3b, v78
	v_mul_f32_e32 v81, 0xbfb8aa3b, v79
	v_exp_f32_e32 v80, v80
	v_exp_f32_e32 v81, v81
	v_add_f32_e32 v80, 1.0, v80
	v_add_f32_e32 v81, 1.0, v81
	v_rcp_f32_e32 v80, v80
	v_rcp_f32_e32 v81, v81
	s_nop 0
	v_pk_mul_f32 v[78:79], v[78:79], v[80:81]
	s_nop 0
	v_pk_mul_f32 v[76:77], v[76:77], v[78:79]
	s_nop 0
	v_cvt_pk_bf16_f32 v75, v76, v77
	v_mul_f32_e32 v76, 0xbfb8aa3b, v70
	v_mul_f32_e32 v77, 0xbfb8aa3b, v71
	v_exp_f32_e32 v76, v76
	v_exp_f32_e32 v77, v77
	v_add_f32_e32 v76, 1.0, v76
	v_add_f32_e32 v77, 1.0, v77
	v_rcp_f32_e32 v76, v76
	v_rcp_f32_e32 v77, v77
	s_nop 0
	v_pk_mul_f32 v[70:71], v[70:71], v[76:77]
	s_nop 0
	v_pk_mul_f32 v[66:67], v[66:67], v[70:71]
	v_pk_mul_f32 v[70:71], v[72:73], v[148:149] op_sel_hi:[1,0]
	v_cvt_pk_bf16_f32 v76, v66, v67
	v_mul_f32_e32 v72, 0xbfb8aa3b, v70
	v_mul_f32_e32 v73, 0xbfb8aa3b, v71
	v_exp_f32_e32 v72, v72
	v_exp_f32_e32 v73, v73
	v_or_b32_e32 v66, 48, v118
	v_mad_i64_i32 v[66:67], s[22:23], v66, s66, v[114:115]
	v_add_f32_e32 v72, 1.0, v72
	v_add_f32_e32 v73, 1.0, v73
	v_rcp_f32_e32 v72, v72
	v_rcp_f32_e32 v73, v73
	v_lshl_add_u64 v[66:67], v[66:67], 0, v[116:117]
	v_pk_mul_f32 v[70:71], v[70:71], v[72:73]
	s_nop 0
	v_pk_mul_f32 v[68:69], v[68:69], v[70:71]
	s_nop 0
	v_cvt_pk_bf16_f32 v77, v68, v69
	global_store_dwordx4 v[66:67], v[74:77], off
	v_mul_f32_e32 v66, 0xbfb8aa3b, v62
	v_mul_f32_e32 v67, 0xbfb8aa3b, v63
	v_exp_f32_e32 v66, v66
	v_exp_f32_e32 v67, v67
	v_add_f32_e32 v66, 1.0, v66
	v_add_f32_e32 v67, 1.0, v67
	v_rcp_f32_e32 v66, v66
	v_rcp_f32_e32 v67, v67
	s_nop 0
	v_pk_mul_f32 v[62:63], v[62:63], v[66:67]
	s_nop 0
	v_pk_mul_f32 v[58:59], v[58:59], v[62:63]
	v_pk_mul_f32 v[62:63], v[64:65], v[146:147] op_sel_hi:[1,0]
	v_cvt_pk_bf16_f32 v58, v58, v59
	v_mul_f32_e32 v64, 0xbfb8aa3b, v62
	v_mul_f32_e32 v65, 0xbfb8aa3b, v63
	v_exp_f32_e32 v64, v64
	v_exp_f32_e32 v65, v65
	v_add_f32_e32 v64, 1.0, v64
	v_add_f32_e32 v65, 1.0, v65
	v_rcp_f32_e32 v64, v64
	v_rcp_f32_e32 v65, v65
	s_nop 0
	v_pk_mul_f32 v[62:63], v[62:63], v[64:65]
	s_nop 0
	v_pk_mul_f32 v[60:61], v[60:61], v[62:63]
	s_nop 0
	v_cvt_pk_bf16_f32 v59, v60, v61
	v_mul_f32_e32 v60, 0xbfb8aa3b, v54
	v_mul_f32_e32 v61, 0xbfb8aa3b, v55
	v_exp_f32_e32 v60, v60
	v_exp_f32_e32 v61, v61
	v_add_f32_e32 v60, 1.0, v60
	v_add_f32_e32 v61, 1.0, v61
	v_rcp_f32_e32 v60, v60
	v_rcp_f32_e32 v61, v61
	s_nop 0
	v_pk_mul_f32 v[54:55], v[54:55], v[60:61]
	s_nop 0
	v_pk_mul_f32 v[50:51], v[50:51], v[54:55]
	v_pk_mul_f32 v[54:55], v[56:57], v[146:147] op_sel_hi:[1,0]
	v_cvt_pk_bf16_f32 v60, v50, v51
	v_mul_f32_e32 v56, 0xbfb8aa3b, v54
	v_mul_f32_e32 v57, 0xbfb8aa3b, v55
	v_exp_f32_e32 v56, v56
	v_exp_f32_e32 v57, v57
	v_add_u32_e32 v50, 0x80, v118
	v_mad_i64_i32 v[50:51], s[22:23], v50, s66, v[114:115]
	v_add_f32_e32 v56, 1.0, v56
	v_add_f32_e32 v57, 1.0, v57
	v_rcp_f32_e32 v56, v56
	v_rcp_f32_e32 v57, v57
	v_lshl_add_u64 v[50:51], v[50:51], 0, v[116:117]
	v_pk_mul_f32 v[54:55], v[54:55], v[56:57]
	s_nop 0
	v_pk_mul_f32 v[52:53], v[52:53], v[54:55]
	s_nop 0
	v_cvt_pk_bf16_f32 v61, v52, v53
	global_store_dwordx4 v[50:51], v[58:61], off
	v_mul_f32_e32 v50, 0xbfb8aa3b, v46
	v_mul_f32_e32 v51, 0xbfb8aa3b, v47
	v_exp_f32_e32 v50, v50
	v_exp_f32_e32 v51, v51
	v_add_f32_e32 v50, 1.0, v50
	v_add_f32_e32 v51, 1.0, v51
	v_rcp_f32_e32 v50, v50
	v_rcp_f32_e32 v51, v51
	s_nop 0
	v_pk_mul_f32 v[46:47], v[46:47], v[50:51]
	s_nop 0
	v_pk_mul_f32 v[42:43], v[42:43], v[46:47]
	v_pk_mul_f32 v[46:47], v[48:49], v[144:145] op_sel_hi:[1,0]
	v_cvt_pk_bf16_f32 v42, v42, v43
	v_mul_f32_e32 v48, 0xbfb8aa3b, v46
	v_mul_f32_e32 v49, 0xbfb8aa3b, v47
	v_exp_f32_e32 v48, v48
	v_exp_f32_e32 v49, v49
	v_add_f32_e32 v48, 1.0, v48
	v_add_f32_e32 v49, 1.0, v49
	v_rcp_f32_e32 v48, v48
	v_rcp_f32_e32 v49, v49
	s_nop 0
	v_pk_mul_f32 v[46:47], v[46:47], v[48:49]
	s_nop 0
	v_pk_mul_f32 v[44:45], v[44:45], v[46:47]
	s_nop 0
	v_cvt_pk_bf16_f32 v43, v44, v45
	v_mul_f32_e32 v44, 0xbfb8aa3b, v38
	v_mul_f32_e32 v45, 0xbfb8aa3b, v39
	v_exp_f32_e32 v44, v44
	v_exp_f32_e32 v45, v45
	v_add_f32_e32 v44, 1.0, v44
	v_add_f32_e32 v45, 1.0, v45
	v_rcp_f32_e32 v44, v44
	v_rcp_f32_e32 v45, v45
	s_nop 0
	v_pk_mul_f32 v[38:39], v[38:39], v[44:45]
	s_nop 0
	v_pk_mul_f32 v[34:35], v[34:35], v[38:39]
	v_pk_mul_f32 v[38:39], v[40:41], v[144:145] op_sel_hi:[1,0]
	v_cvt_pk_bf16_f32 v44, v34, v35
	v_mul_f32_e32 v40, 0xbfb8aa3b, v38
	v_mul_f32_e32 v41, 0xbfb8aa3b, v39
	v_exp_f32_e32 v40, v40
	v_exp_f32_e32 v41, v41
	v_add_u32_e32 v34, 0x90, v118
	v_mad_i64_i32 v[34:35], s[22:23], v34, s66, v[114:115]
	v_add_f32_e32 v40, 1.0, v40
	v_add_f32_e32 v41, 1.0, v41
	v_rcp_f32_e32 v40, v40
	v_rcp_f32_e32 v41, v41
	v_lshl_add_u64 v[34:35], v[34:35], 0, v[116:117]
	v_pk_mul_f32 v[38:39], v[38:39], v[40:41]
	s_nop 0
	v_pk_mul_f32 v[36:37], v[36:37], v[38:39]
	s_nop 0
	v_cvt_pk_bf16_f32 v45, v36, v37
	global_store_dwordx4 v[34:35], v[42:45], off
	s_waitcnt vmcnt(6)
	v_add_f32_e32 v196, v196, v197
	v_add_f32_e32 v198, v198, v199
	v_add_f32_e32 v196, v196, v198
	v_add_f32_e32 v200, v200, v201
	v_add_f32_e32 v206, v206, v207
	v_add_f32_e32 v200, v200, v206
	v_mov_b32_e32 v197, v196
	v_mov_b32_e32 v201, v200
	s_nop 1
	v_permlane16_swap_b32_e32 v196, v197
	v_permlane16_swap_b32_e32 v200, v201
	v_add_f32_e32 v196, v196, v197
	v_add_f32_e32 v200, v200, v201
	v_mov_b32_e32 v197, v196
	v_mov_b32_e32 v201, v200
	s_nop 1
	v_permlane32_swap_b32_e32 v196, v197
	v_permlane32_swap_b32_e32 v200, v201
	v_add_f32_e32 v196, v196, v197
	v_add_f32_e32 v200, v200, v201
	v_fmamk_f32 v196, v196, 0x3a800000, v213
	v_fmamk_f32 v200, v200, 0x3a800000, v213
	v_rsq_f32_e32 v142, v196
	v_rsq_f32_e32 v140, v200
	s_nop 0
	v_pk_mul_f32 v[30:31], v[30:31], v[142:143] op_sel_hi:[1,0]
	v_pk_mul_f32 v[26:27], v[26:27], v[142:143] op_sel_hi:[1,0]
	v_pk_mul_f32 v[28:29], v[28:29], v[142:143] op_sel_hi:[1,0]
	v_pk_mul_f32 v[22:23], v[22:23], v[142:143] op_sel_hi:[1,0]
	v_pk_mul_f32 v[18:19], v[18:19], v[142:143] op_sel_hi:[1,0]
	v_pk_mul_f32 v[20:21], v[20:21], v[142:143] op_sel_hi:[1,0]
	v_pk_mul_f32 v[14:15], v[14:15], v[140:141] op_sel_hi:[1,0]
	v_pk_mul_f32 v[10:11], v[10:11], v[140:141] op_sel_hi:[1,0]
	v_pk_mul_f32 v[12:13], v[12:13], v[140:141] op_sel_hi:[1,0]
	v_pk_mul_f32 v[6:7], v[6:7], v[140:141] op_sel_hi:[1,0]
	v_pk_mul_f32 v[2:3], v[2:3], v[140:141] op_sel_hi:[1,0]
	v_pk_mul_f32 v[4:5], v[4:5], v[140:141] op_sel_hi:[1,0]
	v_mul_f32_e32 v34, 0xbfb8aa3b, v30
	v_mul_f32_e32 v35, 0xbfb8aa3b, v31
	v_exp_f32_e32 v34, v34
	v_exp_f32_e32 v35, v35
	v_add_f32_e32 v34, 1.0, v34
	v_add_f32_e32 v35, 1.0, v35
	v_rcp_f32_e32 v34, v34
	v_rcp_f32_e32 v35, v35
	s_nop 0
	v_pk_mul_f32 v[30:31], v[30:31], v[34:35]
	s_nop 0
	v_pk_mul_f32 v[26:27], v[26:27], v[30:31]
	v_pk_mul_f32 v[30:31], v[32:33], v[142:143] op_sel_hi:[1,0]
	v_cvt_pk_bf16_f32 v26, v26, v27
	v_mul_f32_e32 v32, 0xbfb8aa3b, v30
	v_mul_f32_e32 v33, 0xbfb8aa3b, v31
	v_exp_f32_e32 v32, v32
	v_exp_f32_e32 v33, v33
	v_add_f32_e32 v32, 1.0, v32
	v_add_f32_e32 v33, 1.0, v33
	v_rcp_f32_e32 v32, v32
	v_rcp_f32_e32 v33, v33
	s_nop 0
	v_pk_mul_f32 v[30:31], v[30:31], v[32:33]
	s_nop 0
	v_pk_mul_f32 v[28:29], v[28:29], v[30:31]
	s_nop 0
	v_cvt_pk_bf16_f32 v27, v28, v29
	v_mul_f32_e32 v28, 0xbfb8aa3b, v22
	v_mul_f32_e32 v29, 0xbfb8aa3b, v23
	v_exp_f32_e32 v28, v28
	v_exp_f32_e32 v29, v29
	v_add_f32_e32 v28, 1.0, v28
	v_add_f32_e32 v29, 1.0, v29
	v_rcp_f32_e32 v28, v28
	v_rcp_f32_e32 v29, v29
	s_nop 0
	v_pk_mul_f32 v[22:23], v[22:23], v[28:29]
	s_nop 0
	v_pk_mul_f32 v[18:19], v[18:19], v[22:23]
	v_pk_mul_f32 v[22:23], v[24:25], v[142:143] op_sel_hi:[1,0]
	v_cvt_pk_bf16_f32 v28, v18, v19
	v_mul_f32_e32 v24, 0xbfb8aa3b, v22
	v_mul_f32_e32 v25, 0xbfb8aa3b, v23
	v_exp_f32_e32 v24, v24
	v_exp_f32_e32 v25, v25
	v_add_u32_e32 v18, 0xa0, v118
	v_mad_i64_i32 v[18:19], s[22:23], v18, s66, v[114:115]
	v_add_f32_e32 v24, 1.0, v24
	v_add_f32_e32 v25, 1.0, v25
	v_rcp_f32_e32 v24, v24
	v_rcp_f32_e32 v25, v25
	v_lshl_add_u64 v[18:19], v[18:19], 0, v[116:117]
	v_pk_mul_f32 v[22:23], v[22:23], v[24:25]
	s_nop 0
	v_pk_mul_f32 v[20:21], v[20:21], v[22:23]
	s_nop 0
	v_cvt_pk_bf16_f32 v29, v20, v21
	global_store_dwordx4 v[18:19], v[26:29], off
	v_mul_f32_e32 v18, 0xbfb8aa3b, v14
	v_mul_f32_e32 v19, 0xbfb8aa3b, v15
	v_exp_f32_e32 v18, v18
	v_exp_f32_e32 v19, v19
	v_add_f32_e32 v18, 1.0, v18
	v_add_f32_e32 v19, 1.0, v19
	v_rcp_f32_e32 v18, v18
	v_rcp_f32_e32 v19, v19
	s_nop 0
	v_pk_mul_f32 v[14:15], v[14:15], v[18:19]
	s_nop 0
	v_pk_mul_f32 v[10:11], v[10:11], v[14:15]
	v_pk_mul_f32 v[14:15], v[16:17], v[140:141] op_sel_hi:[1,0]
	v_cvt_pk_bf16_f32 v10, v10, v11
	v_mul_f32_e32 v16, 0xbfb8aa3b, v14
	v_mul_f32_e32 v17, 0xbfb8aa3b, v15
	v_exp_f32_e32 v16, v16
	v_exp_f32_e32 v17, v17
	v_add_f32_e32 v16, 1.0, v16
	v_add_f32_e32 v17, 1.0, v17
	v_rcp_f32_e32 v16, v16
	v_rcp_f32_e32 v17, v17
	s_nop 0
	v_pk_mul_f32 v[14:15], v[14:15], v[16:17]
	s_nop 0
	v_pk_mul_f32 v[12:13], v[12:13], v[14:15]
	s_nop 0
	v_cvt_pk_bf16_f32 v11, v12, v13
	v_mul_f32_e32 v12, 0xbfb8aa3b, v6
	v_mul_f32_e32 v13, 0xbfb8aa3b, v7
	v_exp_f32_e32 v12, v12
	v_exp_f32_e32 v13, v13
	v_add_f32_e32 v12, 1.0, v12
	v_add_f32_e32 v13, 1.0, v13
	v_rcp_f32_e32 v12, v12
	v_rcp_f32_e32 v13, v13
	s_nop 0
	v_pk_mul_f32 v[6:7], v[6:7], v[12:13]
	s_nop 0
	v_pk_mul_f32 v[2:3], v[2:3], v[6:7]
	v_pk_mul_f32 v[6:7], v[8:9], v[140:141] op_sel_hi:[1,0]
	v_cvt_pk_bf16_f32 v12, v2, v3
	v_mul_f32_e32 v8, 0xbfb8aa3b, v6
	v_mul_f32_e32 v9, 0xbfb8aa3b, v7
	v_exp_f32_e32 v8, v8
	v_exp_f32_e32 v9, v9
	v_add_u32_e32 v2, 0xb0, v118
	v_mad_i64_i32 v[2:3], s[22:23], v2, s66, v[114:115]
	v_add_f32_e32 v8, 1.0, v8
	v_add_f32_e32 v9, 1.0, v9
	v_rcp_f32_e32 v8, v8
	v_rcp_f32_e32 v9, v9
	v_lshl_add_u64 v[2:3], v[2:3], 0, v[116:117]
	s_mov_b64 s[22:23], -1
	v_pk_mul_f32 v[6:7], v[6:7], v[8:9]
	s_nop 0
	v_pk_mul_f32 v[4:5], v[4:5], v[6:7]
	s_nop 0
	v_cvt_pk_bf16_f32 v13, v4, v5
	global_store_dwordx4 v[2:3], v[10:13], off
	s_cbranch_vccnz .LBB0_1078
	s_andn2_b64 vcc, exec, s[4:5]
	s_cbranch_vccnz .LBB0_1077
	s_barrier
	s_branch .LBB0_1077

.LBB0_1238:
	s_add_u32 s28, s26, 0xfffc0080
	s_addc_u32 s29, s27, -1
	s_add_i32 s52, 0, 0x10000
	s_cmp_eq_u32 s51, 12
	s_cselect_b32 s31, s15, s29
	s_cselect_b32 s30, s23, s28
	v_add_u32_e32 v140, s52, v141
	s_cselect_b32 s29, s13, s50
	s_cselect_b32 s28, s48, s49
	s_add_i32 s54, 0, 0x14000
	ds_read_b128 v[144:147], v140
	ds_read_b128 v[148:151], v140 offset:1024
	ds_read_b128 v[152:155], v140 offset:2048
	ds_read_b128 v[156:159], v140 offset:3072
	v_add_u32_e32 v140, s54, v141
	ds_read_b128 v[160:163], v140
	ds_read_b128 v[164:167], v140 offset:1024
	ds_read_b128 v[168:171], v140 offset:2048
	ds_read_b128 v[172:175], v140 offset:3072
	v_lshl_add_u64 v[210:211], s[26:27], 0, v[136:137]
	s_add_i32 m0, s25, 0xc000
	ds_read_b128 v[176:179], v143
	ds_read_b128 v[180:183], v143 offset:1024
	ds_read_b128 v[184:187], v143 offset:2048
	ds_read_b128 v[188:191], v143 offset:3072
	ds_read_b128 v[192:195], v143 offset:4096
	ds_read_b128 v[196:199], v143 offset:5120
	ds_read_b128 v[200:203], v143 offset:6144
	ds_read_b128 v[204:207], v143 offset:7168
	global_load_lds_dwordx4 v[210:211], off
	v_lshl_add_u64 v[210:211], s[26:27], 0, v[138:139]
	s_add_i32 m0, s25, 0xe000
	s_nop 0
	global_load_lds_dwordx4 v[210:211], off
	s_waitcnt vmcnt(8)
	s_waitcnt lgkmcnt(0)
	s_barrier
	s_setprio 1
	s_waitcnt lgkmcnt(0)
	v_mfma_f32_16x16x32_bf16 v[126:129], v[144:147], v[176:179], v[126:129]
	v_mfma_f32_16x16x32_bf16 v[118:121], v[152:155], v[176:179], v[118:121]
	v_mfma_f32_16x16x32_bf16 v[110:113], v[144:147], v[184:187], v[110:113]
	v_mfma_f32_16x16x32_bf16 v[102:105], v[152:155], v[184:187], v[102:105]
	v_mfma_f32_16x16x32_bf16 v[94:97], v[144:147], v[192:195], v[94:97]
	v_mfma_f32_16x16x32_bf16 v[86:89], v[152:155], v[192:195], v[86:89]
	v_mfma_f32_16x16x32_bf16 v[78:81], v[144:147], v[200:203], v[78:81]
	v_mfma_f32_16x16x32_bf16 v[70:73], v[152:155], v[200:203], v[70:73]
	v_mfma_f32_16x16x32_bf16 v[126:129], v[148:151], v[180:183], v[126:129]
	v_mfma_f32_16x16x32_bf16 v[118:121], v[156:159], v[180:183], v[118:121]
	v_mfma_f32_16x16x32_bf16 v[110:113], v[148:151], v[188:191], v[110:113]
	v_mfma_f32_16x16x32_bf16 v[102:105], v[156:159], v[188:191], v[102:105]
	v_mfma_f32_16x16x32_bf16 v[94:97], v[148:151], v[196:199], v[94:97]
	v_mfma_f32_16x16x32_bf16 v[86:89], v[156:159], v[196:199], v[86:89]
	v_mfma_f32_16x16x32_bf16 v[78:81], v[148:151], v[204:207], v[78:81]
	v_mfma_f32_16x16x32_bf16 v[70:73], v[156:159], v[204:207], v[70:73]
	s_setprio 0
	s_setprio 1
	v_mfma_f32_16x16x32_bf16 v[122:125], v[160:163], v[176:179], v[122:125]
	v_mfma_f32_16x16x32_bf16 v[114:117], v[168:171], v[176:179], v[114:117]
	v_mfma_f32_16x16x32_bf16 v[106:109], v[160:163], v[184:187], v[106:109]
	v_mfma_f32_16x16x32_bf16 v[98:101], v[168:171], v[184:187], v[98:101]
	v_mfma_f32_16x16x32_bf16 v[90:93], v[160:163], v[192:195], v[90:93]
	v_mfma_f32_16x16x32_bf16 v[82:85], v[168:171], v[192:195], v[82:85]
	v_mfma_f32_16x16x32_bf16 v[74:77], v[160:163], v[200:203], v[74:77]
	v_mfma_f32_16x16x32_bf16 v[66:69], v[168:171], v[200:203], v[66:69]
	v_mfma_f32_16x16x32_bf16 v[122:125], v[164:167], v[180:183], v[122:125]
	v_mfma_f32_16x16x32_bf16 v[114:117], v[172:175], v[180:183], v[114:117]
	v_mfma_f32_16x16x32_bf16 v[106:109], v[164:167], v[188:191], v[106:109]
	v_mfma_f32_16x16x32_bf16 v[98:101], v[172:175], v[188:191], v[98:101]
	v_mfma_f32_16x16x32_bf16 v[90:93], v[164:167], v[196:199], v[90:93]
	v_mfma_f32_16x16x32_bf16 v[82:85], v[172:175], v[196:199], v[82:85]
	v_mfma_f32_16x16x32_bf16 v[74:77], v[164:167], v[204:207], v[74:77]
	v_mfma_f32_16x16x32_bf16 v[66:69], v[172:175], v[204:207], v[66:69]
	s_setprio 0
	s_barrier
	s_add_i32 s52, s52, s39
	v_lshl_add_u64 v[210:211], s[28:29], 0, v[0:1]
	s_mov_b32 m0, s52
	ds_read_b128 v[176:179], v143 offset:16384
	ds_read_b128 v[180:183], v143 offset:17408
	ds_read_b128 v[184:187], v143 offset:18432
	ds_read_b128 v[188:191], v143 offset:19456
	ds_read_b128 v[192:195], v143 offset:20480
	ds_read_b128 v[196:199], v143 offset:21504
	ds_read_b128 v[200:203], v143 offset:22528
	ds_read_b128 v[204:207], v143 offset:23552
	global_load_lds_dwordx4 v[210:211], off
	s_add_i32 m0, s52, 0x2000
	s_add_u32 s52, s28, 0x40000
	v_lshl_add_u64 v[214:215], s[28:29], 0, v[130:131]
	s_addc_u32 s53, s29, 0
	s_add_i32 s54, s54, s39
	global_load_lds_dwordx4 v[214:215], off
	v_lshl_add_u64 v[216:217], s[52:53], 0, v[0:1]
	s_mov_b32 m0, s54
	v_lshl_add_u64 v[224:225], s[30:31], 0, v[132:133]
	global_load_lds_dwordx4 v[216:217], off
	v_lshl_add_u64 v[216:217], s[52:53], 0, v[130:131]
	s_add_i32 m0, s54, 0x2000
	s_nop 0
	global_load_lds_dwordx4 v[216:217], off
	v_lshl_add_u64 v[216:217], s[30:31], 0, v[134:135]
	s_mov_b32 m0, s25
	s_nop 0
	global_load_lds_dwordx4 v[216:217], off
	s_mov_b32 m0, s40
	s_nop 0
	global_load_lds_dwordx4 v[224:225], off
	s_cmp_lg_u32 s51, 12
	s_cbranch_scc1 .Lp3r_nlA
	s_lshl_b32 s54, s22, 8
	s_add_i32 s54, s54, s43
	v_and_b32_e32 v228, 15, v212
	v_lshrrev_b32_e32 v229, 4, v212
	v_or_b32_e32 v228, s54, v228
	v_lshlrev_b32_e32 v228, 6, v228
	v_lshl_add_u32 v230, v229, 4, v228
	v_mov_b32_e32 v231, 0
	v_lshl_add_u64 v[250:251], s[4:5], 0, v[230:231]
	v_mov_b32_e32 v230, 0x2000
	v_lshl_add_u64 v[248:249], v[250:251], 0, v[230:231]
	global_load_dwordx4 v[228:231], v[250:251], off
	global_load_dwordx4 v[232:235], v[250:251], off offset:1024
	global_load_dwordx4 v[236:239], v[250:251], off offset:2048
	global_load_dwordx4 v[240:243], v[250:251], off offset:3072
	global_load_dwordx4 v[244:247], v[248:249], off
	s_nop 0
	global_load_dwordx4 v[248:251], v[248:249], off offset:1024
	s_waitcnt vmcnt(14)
	s_branch .Lp3r_jA

.Lp3r_jA:
	s_waitcnt lgkmcnt(0)
	s_barrier
	s_setprio 1
	s_waitcnt lgkmcnt(0)
	v_mfma_f32_16x16x32_bf16 v[62:65], v[144:147], v[176:179], v[62:65]
	v_mfma_f32_16x16x32_bf16 v[54:57], v[152:155], v[176:179], v[54:57]
	v_mfma_f32_16x16x32_bf16 v[46:49], v[144:147], v[184:187], v[46:49]
	v_mfma_f32_16x16x32_bf16 v[38:41], v[152:155], v[184:187], v[38:41]
	v_mfma_f32_16x16x32_bf16 v[30:33], v[144:147], v[192:195], v[30:33]
	v_mfma_f32_16x16x32_bf16 v[22:25], v[152:155], v[192:195], v[22:25]
	v_mfma_f32_16x16x32_bf16 v[14:17], v[144:147], v[200:203], v[14:17]
	v_mfma_f32_16x16x32_bf16 v[6:9], v[152:155], v[200:203], v[6:9]
	v_mfma_f32_16x16x32_bf16 v[62:65], v[148:151], v[180:183], v[62:65]
	v_mfma_f32_16x16x32_bf16 v[54:57], v[156:159], v[180:183], v[54:57]
	v_mfma_f32_16x16x32_bf16 v[46:49], v[148:151], v[188:191], v[46:49]
	v_mfma_f32_16x16x32_bf16 v[38:41], v[156:159], v[188:191], v[38:41]
	v_mfma_f32_16x16x32_bf16 v[30:33], v[148:151], v[196:199], v[30:33]
	v_mfma_f32_16x16x32_bf16 v[22:25], v[156:159], v[196:199], v[22:25]
	v_mfma_f32_16x16x32_bf16 v[14:17], v[148:151], v[204:207], v[14:17]
	v_mfma_f32_16x16x32_bf16 v[6:9], v[156:159], v[204:207], v[6:9]
	s_setprio 0
	s_setprio 1
	v_mfma_f32_16x16x32_bf16 v[58:61], v[160:163], v[176:179], v[58:61]
	v_mfma_f32_16x16x32_bf16 v[50:53], v[168:171], v[176:179], v[50:53]
	v_mfma_f32_16x16x32_bf16 v[42:45], v[160:163], v[184:187], v[42:45]
	v_mfma_f32_16x16x32_bf16 v[34:37], v[168:171], v[184:187], v[34:37]
	v_mfma_f32_16x16x32_bf16 v[26:29], v[160:163], v[192:195], v[26:29]
	v_mfma_f32_16x16x32_bf16 v[18:21], v[168:171], v[192:195], v[18:21]
	v_mfma_f32_16x16x32_bf16 v[10:13], v[160:163], v[200:203], v[10:13]
	v_mfma_f32_16x16x32_bf16 v[2:5], v[168:171], v[200:203], v[2:5]
	v_mfma_f32_16x16x32_bf16 v[58:61], v[164:167], v[180:183], v[58:61]
	v_mfma_f32_16x16x32_bf16 v[50:53], v[172:175], v[180:183], v[50:53]
	v_mfma_f32_16x16x32_bf16 v[42:45], v[164:167], v[188:191], v[42:45]
	v_mfma_f32_16x16x32_bf16 v[34:37], v[172:175], v[188:191], v[34:37]
	v_mfma_f32_16x16x32_bf16 v[26:29], v[164:167], v[196:199], v[26:29]
	v_mfma_f32_16x16x32_bf16 v[18:21], v[172:175], v[196:199], v[18:21]
	v_mfma_f32_16x16x32_bf16 v[10:13], v[164:167], v[204:207], v[10:13]
	v_mfma_f32_16x16x32_bf16 v[2:5], v[172:175], v[204:207], v[2:5]
	s_setprio 0
	s_barrier
	s_add_i32 s52, 0, 0x18000
	v_add_u32_e32 v140, s52, v141
	s_add_i32 s53, 0, 0x1c000
	ds_read_b128 v[144:147], v140
	ds_read_b128 v[148:151], v140 offset:1024
	ds_read_b128 v[152:155], v140 offset:2048
	ds_read_b128 v[156:159], v140 offset:3072
	v_add_u32_e32 v140, s53, v141
	ds_read_b128 v[160:163], v140
	ds_read_b128 v[164:167], v140 offset:1024
	ds_read_b128 v[168:171], v140 offset:2048
	ds_read_b128 v[172:175], v140 offset:3072
	s_add_u32 s30, s30, 0x40000
	s_addc_u32 s31, s31, 0
	s_mov_b32 m0, s41
	v_lshl_add_u64 v[226:227], s[30:31], 0, v[134:135]
	ds_read_b128 v[176:179], v143 offset:32768
	ds_read_b128 v[180:183], v143 offset:33792
	ds_read_b128 v[184:187], v143 offset:34816
	ds_read_b128 v[188:191], v143 offset:35840
	ds_read_b128 v[192:195], v143 offset:36864
	ds_read_b128 v[196:199], v143 offset:37888
	ds_read_b128 v[200:203], v143 offset:38912
	ds_read_b128 v[204:207], v143 offset:39936
	global_load_lds_dwordx4 v[226:227], off
	v_lshl_add_u64 v[226:227], s[30:31], 0, v[132:133]
	s_mov_b32 m0, s42
	s_nop 0
	global_load_lds_dwordx4 v[226:227], off
	s_cmp_lg_u32 s51, 12
	s_cbranch_scc1 .Lp3r_nlB
	s_waitcnt vmcnt(14)
	s_branch .Lp3r_jB

.Lp3r_jB:
	s_waitcnt lgkmcnt(0)
	s_barrier
	s_setprio 1
	s_waitcnt lgkmcnt(0)
	v_mfma_f32_16x16x32_bf16 v[126:129], v[144:147], v[176:179], v[126:129]
	v_mfma_f32_16x16x32_bf16 v[118:121], v[152:155], v[176:179], v[118:121]
	v_mfma_f32_16x16x32_bf16 v[110:113], v[144:147], v[184:187], v[110:113]
	v_mfma_f32_16x16x32_bf16 v[102:105], v[152:155], v[184:187], v[102:105]
	v_mfma_f32_16x16x32_bf16 v[94:97], v[144:147], v[192:195], v[94:97]
	v_mfma_f32_16x16x32_bf16 v[86:89], v[152:155], v[192:195], v[86:89]
	v_mfma_f32_16x16x32_bf16 v[78:81], v[144:147], v[200:203], v[78:81]
	v_mfma_f32_16x16x32_bf16 v[70:73], v[152:155], v[200:203], v[70:73]
	v_mfma_f32_16x16x32_bf16 v[126:129], v[148:151], v[180:183], v[126:129]
	v_mfma_f32_16x16x32_bf16 v[118:121], v[156:159], v[180:183], v[118:121]
	v_mfma_f32_16x16x32_bf16 v[110:113], v[148:151], v[188:191], v[110:113]
	v_mfma_f32_16x16x32_bf16 v[102:105], v[156:159], v[188:191], v[102:105]
	v_mfma_f32_16x16x32_bf16 v[94:97], v[148:151], v[196:199], v[94:97]
	v_mfma_f32_16x16x32_bf16 v[86:89], v[156:159], v[196:199], v[86:89]
	v_mfma_f32_16x16x32_bf16 v[78:81], v[148:151], v[204:207], v[78:81]
	v_mfma_f32_16x16x32_bf16 v[70:73], v[156:159], v[204:207], v[70:73]
	s_setprio 0
	s_setprio 1
	v_mfma_f32_16x16x32_bf16 v[122:125], v[160:163], v[176:179], v[122:125]
	v_mfma_f32_16x16x32_bf16 v[114:117], v[168:171], v[176:179], v[114:117]
	v_mfma_f32_16x16x32_bf16 v[106:109], v[160:163], v[184:187], v[106:109]
	v_mfma_f32_16x16x32_bf16 v[98:101], v[168:171], v[184:187], v[98:101]
	v_mfma_f32_16x16x32_bf16 v[90:93], v[160:163], v[192:195], v[90:93]
	v_mfma_f32_16x16x32_bf16 v[82:85], v[168:171], v[192:195], v[82:85]
	v_mfma_f32_16x16x32_bf16 v[74:77], v[160:163], v[200:203], v[74:77]
	v_mfma_f32_16x16x32_bf16 v[66:69], v[168:171], v[200:203], v[66:69]
	v_mfma_f32_16x16x32_bf16 v[122:125], v[164:167], v[180:183], v[122:125]
	v_mfma_f32_16x16x32_bf16 v[114:117], v[172:175], v[180:183], v[114:117]
	v_mfma_f32_16x16x32_bf16 v[106:109], v[164:167], v[188:191], v[106:109]
	v_mfma_f32_16x16x32_bf16 v[98:101], v[172:175], v[188:191], v[98:101]
	v_mfma_f32_16x16x32_bf16 v[90:93], v[164:167], v[196:199], v[90:93]
	v_mfma_f32_16x16x32_bf16 v[82:85], v[172:175], v[196:199], v[82:85]
	v_mfma_f32_16x16x32_bf16 v[74:77], v[164:167], v[204:207], v[74:77]
	v_mfma_f32_16x16x32_bf16 v[66:69], v[172:175], v[204:207], v[66:69]
	s_setprio 0
	s_barrier
	s_add_i32 s30, s52, s39
	v_lshl_add_u64 v[210:211], v[210:211], 0, s[94:95]
	s_mov_b32 m0, s30
	ds_read_b128 v[176:179], v143 offset:49152
	ds_read_b128 v[180:183], v143 offset:50176
	ds_read_b128 v[184:187], v143 offset:51200
	ds_read_b128 v[188:191], v143 offset:52224
	ds_read_b128 v[192:195], v143 offset:53248
	ds_read_b128 v[196:199], v143 offset:54272
	ds_read_b128 v[200:203], v143 offset:55296
	ds_read_b128 v[204:207], v143 offset:56320
	global_load_lds_dwordx4 v[210:211], off
	s_add_i32 m0, s30, 0x2000
	s_add_u32 s28, s28, 0x40080
	v_lshl_add_u64 v[210:211], v[214:215], 0, s[94:95]
	s_addc_u32 s29, s29, 0
	s_add_i32 s30, s53, s39
	global_load_lds_dwordx4 v[210:211], off
	v_lshl_add_u64 v[210:211], s[28:29], 0, v[0:1]
	s_mov_b32 m0, s30
	s_nop 0
	global_load_lds_dwordx4 v[210:211], off
	v_lshl_add_u64 v[210:211], s[28:29], 0, v[130:131]
	s_add_i32 m0, s30, 0x2000
	s_nop 0
	global_load_lds_dwordx4 v[210:211], off
	v_lshl_add_u64 v[210:211], v[216:217], 0, s[94:95]
	s_mov_b32 m0, s45
	s_nop 0
	global_load_lds_dwordx4 v[210:211], off
	v_lshl_add_u64 v[210:211], v[224:225], 0, s[94:95]
	s_mov_b32 m0, s46
	s_nop 0
	global_load_lds_dwordx4 v[210:211], off
	s_cmp_lg_u32 s51, 12
	s_cbranch_scc1 .Lp3r_nlC
	s_lshl_b32 s54, s22, 8
	s_add_i32 s54, s54, s43
	v_and_b32_e32 v214, 15, v212
	v_lshrrev_b32_e32 v215, 4, v212
	v_or_b32_e32 v214, s54, v214
	v_lshlrev_b32_e32 v214, 6, v214
	v_lshl_add_u32 v214, v215, 4, v214
	v_add_u32_e32 v214, 0x2800, v214
	v_mov_b32_e32 v215, 0
	v_lshl_add_u64 v[210:211], s[4:5], 0, v[214:215]
	global_load_dwordx4 v[214:217], v[210:211], off
	global_load_dwordx4 v[224:227], v[210:211], off offset:1024
	s_waitcnt vmcnt(16)
	s_branch .Lp3r_jC

.Lp3r_jC:
	s_waitcnt lgkmcnt(0)
	s_barrier
	s_setprio 1
	s_waitcnt lgkmcnt(0)
	v_mfma_f32_16x16x32_bf16 v[62:65], v[144:147], v[176:179], v[62:65]
	v_mfma_f32_16x16x32_bf16 v[54:57], v[152:155], v[176:179], v[54:57]
	v_mfma_f32_16x16x32_bf16 v[46:49], v[144:147], v[184:187], v[46:49]
	v_mfma_f32_16x16x32_bf16 v[38:41], v[152:155], v[184:187], v[38:41]
	v_mfma_f32_16x16x32_bf16 v[30:33], v[144:147], v[192:195], v[30:33]
	v_mfma_f32_16x16x32_bf16 v[22:25], v[152:155], v[192:195], v[22:25]
	v_mfma_f32_16x16x32_bf16 v[14:17], v[144:147], v[200:203], v[14:17]
	v_mfma_f32_16x16x32_bf16 v[6:9], v[152:155], v[200:203], v[6:9]
	v_mfma_f32_16x16x32_bf16 v[62:65], v[148:151], v[180:183], v[62:65]
	v_mfma_f32_16x16x32_bf16 v[54:57], v[156:159], v[180:183], v[54:57]
	v_mfma_f32_16x16x32_bf16 v[46:49], v[148:151], v[188:191], v[46:49]
	v_mfma_f32_16x16x32_bf16 v[38:41], v[156:159], v[188:191], v[38:41]
	v_mfma_f32_16x16x32_bf16 v[30:33], v[148:151], v[196:199], v[30:33]
	v_mfma_f32_16x16x32_bf16 v[22:25], v[156:159], v[196:199], v[22:25]
	v_mfma_f32_16x16x32_bf16 v[14:17], v[148:151], v[204:207], v[14:17]
	v_mfma_f32_16x16x32_bf16 v[6:9], v[156:159], v[204:207], v[6:9]
	s_setprio 0
	s_setprio 1
	v_mfma_f32_16x16x32_bf16 v[58:61], v[160:163], v[176:179], v[58:61]
	v_mfma_f32_16x16x32_bf16 v[50:53], v[168:171], v[176:179], v[50:53]
	v_mfma_f32_16x16x32_bf16 v[42:45], v[160:163], v[184:187], v[42:45]
	v_mfma_f32_16x16x32_bf16 v[34:37], v[168:171], v[184:187], v[34:37]
	v_mfma_f32_16x16x32_bf16 v[26:29], v[160:163], v[192:195], v[26:29]
	v_mfma_f32_16x16x32_bf16 v[18:21], v[168:171], v[192:195], v[18:21]
	v_mfma_f32_16x16x32_bf16 v[10:13], v[160:163], v[200:203], v[10:13]
	v_mfma_f32_16x16x32_bf16 v[2:5], v[168:171], v[200:203], v[2:5]
	v_mfma_f32_16x16x32_bf16 v[58:61], v[164:167], v[180:183], v[58:61]
	v_mfma_f32_16x16x32_bf16 v[50:53], v[172:175], v[180:183], v[50:53]
	v_mfma_f32_16x16x32_bf16 v[42:45], v[164:167], v[188:191], v[42:45]
	v_mfma_f32_16x16x32_bf16 v[34:37], v[172:175], v[188:191], v[34:37]
	v_mfma_f32_16x16x32_bf16 v[26:29], v[164:167], v[196:199], v[26:29]
	v_mfma_f32_16x16x32_bf16 v[18:21], v[172:175], v[196:199], v[18:21]
	v_mfma_f32_16x16x32_bf16 v[10:13], v[164:167], v[204:207], v[10:13]
	v_mfma_f32_16x16x32_bf16 v[2:5], v[172:175], v[204:207], v[2:5]
	s_setprio 0
	s_barrier
	s_add_i32 s51, s51, 2
	s_add_u32 s26, s26, 0x100
	s_addc_u32 s27, s27, 0
	s_add_u32 s49, s49, 0x100
	s_addc_u32 s50, s50, 0
	s_cmp_gt_u32 s51, 13
	s_cbranch_scc0 .LBB0_1238
	v_mov_b32_e32 v140, v212
	s_lshl_b32 s13, s24, 7
	v_and_b32_e32 v153, 15, v140
	v_ashrrev_i32_e32 v140, 4, v140
	s_or_b32 s13, s13, s44
	v_lshl_add_u32 v152, v140, 3, s13
	s_lshl_b32 s13, s22, 8
	s_movk_i32 s15, 0x2000
	s_and_b64 vcc, exec, s[8:9]
	s_cbranch_vccz .LBB0_1241
	s_barrier
.LBB0_1241:
	s_andn2_b64 vcc, exec, s[16:17]
	s_waitcnt vmcnt(10)
	v_add_f32_e32 v140, v228, v229
	v_add_f32_e32 v142, v230, v231
	v_add_f32_e32 v140, v140, v142
	v_add_f32_e32 v142, v232, v233
	v_add_f32_e32 v144, v234, v235
	v_add_f32_e32 v142, v142, v144
	v_add_f32_e32 v144, v236, v237
	v_add_f32_e32 v145, v238, v239
	v_add_f32_e32 v144, v144, v145
	v_add_f32_e32 v145, v240, v241
	v_add_f32_e32 v146, v242, v243
	v_add_f32_e32 v145, v145, v146
	v_add_f32_e32 v146, v244, v245
	v_add_f32_e32 v147, v246, v247
	v_add_f32_e32 v146, v146, v147
	v_add_f32_e32 v147, v248, v249
	v_add_f32_e32 v148, v250, v251
	v_add_f32_e32 v147, v147, v148
	v_mov_b32_e32 v150, v140
	s_nop 1
	v_permlane16_swap_b32_e32 v140, v150
	v_add_f32_e32 v140, v140, v150
	v_mov_b32_e32 v150, v142
	s_nop 1
	v_permlane16_swap_b32_e32 v142, v150
	v_add_f32_e32 v142, v142, v150
	v_mov_b32_e32 v150, v144
	s_nop 1
	v_permlane16_swap_b32_e32 v144, v150
	v_add_f32_e32 v144, v144, v150
	v_mov_b32_e32 v150, v145
	s_nop 1
	v_permlane16_swap_b32_e32 v145, v150
	v_add_f32_e32 v145, v145, v150
	v_mov_b32_e32 v150, v146
	s_nop 1
	v_permlane16_swap_b32_e32 v146, v150
	v_add_f32_e32 v146, v146, v150
	v_mov_b32_e32 v150, v147
	s_nop 1
	v_permlane16_swap_b32_e32 v147, v150
	v_add_f32_e32 v147, v147, v150
	v_mov_b32_e32 v150, v140
	s_nop 1
	v_permlane32_swap_b32_e32 v140, v150
	v_add_f32_e32 v140, v140, v150
	v_mov_b32_e32 v150, v142
	s_nop 1
	v_permlane32_swap_b32_e32 v142, v150
	v_add_f32_e32 v142, v142, v150
	v_mov_b32_e32 v150, v144
	s_nop 1
	v_permlane32_swap_b32_e32 v144, v150
	v_add_f32_e32 v144, v144, v150
	v_mov_b32_e32 v150, v145
	s_nop 1
	v_permlane32_swap_b32_e32 v145, v150
	v_add_f32_e32 v145, v145, v150
	v_mov_b32_e32 v150, v146
	s_nop 1
	v_permlane32_swap_b32_e32 v146, v150
	v_add_f32_e32 v146, v146, v150
	v_mov_b32_e32 v150, v147
	s_nop 1
	v_permlane32_swap_b32_e32 v147, v150
	v_fmamk_f32 v140, v140, 0x3a800000, v213
	v_add_f32_e32 v147, v147, v150
	v_rsq_f32_e32 v156, v140
	s_nop 0
	v_fmamk_f32 v140, v142, 0x3a800000, v213
	v_rsq_f32_e32 v154, v140
	v_fmamk_f32 v140, v144, 0x3a800000, v213
	v_rsq_f32_e32 v150, v140
	v_fmamk_f32 v140, v145, 0x3a800000, v213
	v_rsq_f32_e32 v148, v140
	v_fmamk_f32 v140, v146, 0x3a800000, v213
	v_pk_mul_f32 v[126:127], v[126:127], v[156:157] op_sel_hi:[1,0]
	v_rsq_f32_e32 v146, v140
	v_fmamk_f32 v140, v147, 0x3a800000, v213
	v_mul_f32_e32 v147, 0xbfb8aa3b, v126
	v_exp_f32_e32 v147, v147
	v_pk_mul_f32 v[122:123], v[122:123], v[156:157] op_sel_hi:[1,0]
	v_pk_mul_f32 v[124:125], v[124:125], v[156:157] op_sel_hi:[1,0]
	v_pk_mul_f32 v[118:119], v[118:119], v[156:157] op_sel_hi:[1,0]
	v_add_f32_e32 v147, 1.0, v147
	v_rcp_f32_e32 v158, v147
	v_mul_f32_e32 v147, 0xbfb8aa3b, v127
	v_exp_f32_e32 v147, v147
	v_pk_mul_f32 v[114:115], v[114:115], v[156:157] op_sel_hi:[1,0]
	v_pk_mul_f32 v[116:117], v[116:117], v[156:157] op_sel_hi:[1,0]
	v_pk_mul_f32 v[110:111], v[110:111], v[154:155] op_sel_hi:[1,0]
	v_add_f32_e32 v147, 1.0, v147
	v_rcp_f32_e32 v159, v147
	v_or_b32_e32 v145, s43, v153
	v_ashrrev_i32_e32 v153, 31, v152
	v_pk_mul_f32 v[106:107], v[106:107], v[154:155] op_sel_hi:[1,0]
	v_pk_mul_f32 v[126:127], v[126:127], v[158:159]
	v_pk_mul_f32 v[108:109], v[108:109], v[154:155] op_sel_hi:[1,0]
	v_pk_mul_f32 v[122:123], v[122:123], v[126:127]
	v_pk_mul_f32 v[126:127], v[128:129], v[156:157] op_sel_hi:[1,0]
	v_cvt_pk_bf16_f32 v122, v122, v123
	v_mul_f32_e32 v128, 0xbfb8aa3b, v126
	v_mul_f32_e32 v129, 0xbfb8aa3b, v127
	v_exp_f32_e32 v128, v128
	v_exp_f32_e32 v129, v129
	v_pk_mul_f32 v[102:103], v[102:103], v[154:155] op_sel_hi:[1,0]
	v_pk_mul_f32 v[98:99], v[98:99], v[154:155] op_sel_hi:[1,0]
	v_add_f32_e32 v128, 1.0, v128
	v_add_f32_e32 v129, 1.0, v129
	v_rcp_f32_e32 v128, v128
	v_rcp_f32_e32 v129, v129
	v_pk_mul_f32 v[100:101], v[100:101], v[154:155] op_sel_hi:[1,0]
	v_pk_mul_f32 v[94:95], v[94:95], v[150:151] op_sel_hi:[1,0]
	v_pk_mul_f32 v[90:91], v[90:91], v[150:151] op_sel_hi:[1,0]
	v_pk_mul_f32 v[126:127], v[126:127], v[128:129]
	v_pk_mul_f32 v[92:93], v[92:93], v[150:151] op_sel_hi:[1,0]
	v_pk_mul_f32 v[124:125], v[124:125], v[126:127]
	v_pk_mul_f32 v[86:87], v[86:87], v[150:151] op_sel_hi:[1,0]
	v_cvt_pk_bf16_f32 v123, v124, v125
	v_mul_f32_e32 v124, 0xbfb8aa3b, v118
	v_mul_f32_e32 v125, 0xbfb8aa3b, v119
	v_exp_f32_e32 v124, v124
	v_exp_f32_e32 v125, v125
	v_pk_mul_f32 v[82:83], v[82:83], v[150:151] op_sel_hi:[1,0]
	v_pk_mul_f32 v[84:85], v[84:85], v[150:151] op_sel_hi:[1,0]
	v_add_f32_e32 v124, 1.0, v124
	v_add_f32_e32 v125, 1.0, v125
	v_rcp_f32_e32 v124, v124
	v_rcp_f32_e32 v125, v125
	v_pk_mul_f32 v[78:79], v[78:79], v[148:149] op_sel_hi:[1,0]
	v_pk_mul_f32 v[74:75], v[74:75], v[148:149] op_sel_hi:[1,0]
	v_pk_mul_f32 v[76:77], v[76:77], v[148:149] op_sel_hi:[1,0]
	v_pk_mul_f32 v[118:119], v[118:119], v[124:125]
	v_pk_mul_f32 v[70:71], v[70:71], v[148:149] op_sel_hi:[1,0]
	v_pk_mul_f32 v[114:115], v[114:115], v[118:119]
	v_pk_mul_f32 v[118:119], v[120:121], v[156:157] op_sel_hi:[1,0]
	v_cvt_pk_bf16_f32 v124, v114, v115
	v_mul_f32_e32 v120, 0xbfb8aa3b, v118
	v_mul_f32_e32 v121, 0xbfb8aa3b, v119
	v_exp_f32_e32 v120, v120
	v_exp_f32_e32 v121, v121
	v_mov_b64_e32 v[114:115], s[6:7]
	v_pk_mul_f32 v[66:67], v[66:67], v[148:149] op_sel_hi:[1,0]
	v_add_f32_e32 v120, 1.0, v120
	v_add_f32_e32 v121, 1.0, v121
	v_rcp_f32_e32 v120, v120
	v_rcp_f32_e32 v121, v121
	v_pk_mul_f32 v[68:69], v[68:69], v[148:149] op_sel_hi:[1,0]
	v_pk_mul_f32 v[62:63], v[62:63], v[146:147] op_sel_hi:[1,0]
	v_pk_mul_f32 v[58:59], v[58:59], v[146:147] op_sel_hi:[1,0]
	v_pk_mul_f32 v[118:119], v[118:119], v[120:121]
	v_pk_mul_f32 v[60:61], v[60:61], v[146:147] op_sel_hi:[1,0]
	v_pk_mul_f32 v[116:117], v[116:117], v[118:119]
	v_mul_f32_e32 v119, 0xbfb8aa3b, v110
	v_exp_f32_e32 v119, v119
	v_add_u32_e32 v118, s13, v145
	v_cvt_pk_bf16_f32 v125, v116, v117
	v_mad_i64_i32 v[120:121], s[22:23], v118, s66, v[114:115]
	v_lshlrev_b64 v[116:117], 1, v[152:153]
	v_lshl_add_u64 v[120:121], v[120:121], 0, v[116:117]
	v_add_f32_e32 v119, 1.0, v119
	global_store_dwordx4 v[120:121], v[122:125], off
	v_rcp_f32_e32 v120, v119
	v_mul_f32_e32 v119, 0xbfb8aa3b, v111
	v_exp_f32_e32 v119, v119
	v_pk_mul_f32 v[54:55], v[54:55], v[146:147] op_sel_hi:[1,0]
	v_pk_mul_f32 v[50:51], v[50:51], v[146:147] op_sel_hi:[1,0]
	v_rsq_f32_e32 v144, v140
	v_add_f32_e32 v119, 1.0, v119
	v_rcp_f32_e32 v121, v119
	v_pk_mul_f32 v[52:53], v[52:53], v[146:147] op_sel_hi:[1,0]
	v_pk_mul_f32 v[46:47], v[46:47], v[144:145] op_sel_hi:[1,0]
	v_pk_mul_f32 v[42:43], v[42:43], v[144:145] op_sel_hi:[1,0]
	v_pk_mul_f32 v[110:111], v[110:111], v[120:121]
	v_pk_mul_f32 v[44:45], v[44:45], v[144:145] op_sel_hi:[1,0]
	v_pk_mul_f32 v[106:107], v[106:107], v[110:111]
	v_pk_mul_f32 v[110:111], v[112:113], v[154:155] op_sel_hi:[1,0]
	v_cvt_pk_bf16_f32 v106, v106, v107
	v_mul_f32_e32 v112, 0xbfb8aa3b, v110
	v_mul_f32_e32 v113, 0xbfb8aa3b, v111
	v_exp_f32_e32 v112, v112
	v_exp_f32_e32 v113, v113
	v_pk_mul_f32 v[38:39], v[38:39], v[144:145] op_sel_hi:[1,0]
	v_pk_mul_f32 v[34:35], v[34:35], v[144:145] op_sel_hi:[1,0]
	v_add_f32_e32 v112, 1.0, v112
	v_add_f32_e32 v113, 1.0, v113
	v_rcp_f32_e32 v112, v112
	v_rcp_f32_e32 v113, v113
	v_pk_mul_f32 v[36:37], v[36:37], v[144:145] op_sel_hi:[1,0]
	v_pk_mul_f32 v[110:111], v[110:111], v[112:113]
	v_pk_mul_f32 v[108:109], v[108:109], v[110:111]
	v_cvt_pk_bf16_f32 v107, v108, v109
	v_mul_f32_e32 v108, 0xbfb8aa3b, v102
	v_mul_f32_e32 v109, 0xbfb8aa3b, v103
	v_exp_f32_e32 v108, v108
	v_exp_f32_e32 v109, v109
	v_add_f32_e32 v108, 1.0, v108
	v_add_f32_e32 v109, 1.0, v109
	v_rcp_f32_e32 v108, v108
	v_rcp_f32_e32 v109, v109
	s_nop 0
	v_pk_mul_f32 v[102:103], v[102:103], v[108:109]
	v_pk_mul_f32 v[98:99], v[98:99], v[102:103]
	v_pk_mul_f32 v[102:103], v[104:105], v[154:155] op_sel_hi:[1,0]
	v_cvt_pk_bf16_f32 v108, v98, v99
	v_mul_f32_e32 v104, 0xbfb8aa3b, v102
	v_mul_f32_e32 v105, 0xbfb8aa3b, v103
	v_exp_f32_e32 v104, v104
	v_exp_f32_e32 v105, v105
	v_or_b32_e32 v98, 16, v118
	v_mad_i64_i32 v[98:99], s[22:23], v98, s66, v[114:115]
	v_add_f32_e32 v104, 1.0, v104
	v_add_f32_e32 v105, 1.0, v105
	v_rcp_f32_e32 v104, v104
	v_rcp_f32_e32 v105, v105
	v_lshl_add_u64 v[98:99], v[98:99], 0, v[116:117]
	v_pk_mul_f32 v[102:103], v[102:103], v[104:105]
	v_pk_mul_f32 v[100:101], v[100:101], v[102:103]
	v_cvt_pk_bf16_f32 v109, v100, v101
	global_store_dwordx4 v[98:99], v[106:109], off
	v_mul_f32_e32 v98, 0xbfb8aa3b, v94
	v_mul_f32_e32 v99, 0xbfb8aa3b, v95
	v_exp_f32_e32 v98, v98
	v_exp_f32_e32 v99, v99
	v_add_f32_e32 v98, 1.0, v98
	v_add_f32_e32 v99, 1.0, v99
	v_rcp_f32_e32 v98, v98
	v_rcp_f32_e32 v99, v99
	s_nop 0
	v_pk_mul_f32 v[94:95], v[94:95], v[98:99]
	s_nop 0
	v_pk_mul_f32 v[90:91], v[90:91], v[94:95]
	v_pk_mul_f32 v[94:95], v[96:97], v[150:151] op_sel_hi:[1,0]
	v_cvt_pk_bf16_f32 v90, v90, v91
	v_mul_f32_e32 v96, 0xbfb8aa3b, v94
	v_mul_f32_e32 v97, 0xbfb8aa3b, v95
	v_exp_f32_e32 v96, v96
	v_exp_f32_e32 v97, v97
	v_add_f32_e32 v96, 1.0, v96
	v_add_f32_e32 v97, 1.0, v97
	v_rcp_f32_e32 v96, v96
	v_rcp_f32_e32 v97, v97
	s_nop 0
	v_pk_mul_f32 v[94:95], v[94:95], v[96:97]
	s_nop 0
	v_pk_mul_f32 v[92:93], v[92:93], v[94:95]
	s_nop 0
	v_cvt_pk_bf16_f32 v91, v92, v93
	v_mul_f32_e32 v92, 0xbfb8aa3b, v86
	v_mul_f32_e32 v93, 0xbfb8aa3b, v87
	v_exp_f32_e32 v92, v92
	v_exp_f32_e32 v93, v93
	v_add_f32_e32 v92, 1.0, v92
	v_add_f32_e32 v93, 1.0, v93
	v_rcp_f32_e32 v92, v92
	v_rcp_f32_e32 v93, v93
	s_nop 0
	v_pk_mul_f32 v[86:87], v[86:87], v[92:93]
	s_nop 0
	v_pk_mul_f32 v[82:83], v[82:83], v[86:87]
	v_pk_mul_f32 v[86:87], v[88:89], v[150:151] op_sel_hi:[1,0]
	v_cvt_pk_bf16_f32 v92, v82, v83
	v_mul_f32_e32 v88, 0xbfb8aa3b, v86
	v_mul_f32_e32 v89, 0xbfb8aa3b, v87
	v_exp_f32_e32 v88, v88
	v_exp_f32_e32 v89, v89
	v_or_b32_e32 v82, 32, v118
	v_mad_i64_i32 v[82:83], s[22:23], v82, s66, v[114:115]
	v_add_f32_e32 v88, 1.0, v88
	v_add_f32_e32 v89, 1.0, v89
	v_rcp_f32_e32 v88, v88
	v_rcp_f32_e32 v89, v89
	v_lshl_add_u64 v[82:83], v[82:83], 0, v[116:117]
	v_pk_mul_f32 v[86:87], v[86:87], v[88:89]
	s_nop 0
	v_pk_mul_f32 v[84:85], v[84:85], v[86:87]
	s_nop 0
	v_cvt_pk_bf16_f32 v93, v84, v85
	global_store_dwordx4 v[82:83], v[90:93], off
	v_mul_f32_e32 v82, 0xbfb8aa3b, v78
	v_mul_f32_e32 v83, 0xbfb8aa3b, v79
	v_exp_f32_e32 v82, v82
	v_exp_f32_e32 v83, v83
	v_add_f32_e32 v82, 1.0, v82
	v_add_f32_e32 v83, 1.0, v83
	v_rcp_f32_e32 v82, v82
	v_rcp_f32_e32 v83, v83
	s_nop 0
	v_pk_mul_f32 v[78:79], v[78:79], v[82:83]
	s_nop 0
	v_pk_mul_f32 v[74:75], v[74:75], v[78:79]
	v_pk_mul_f32 v[78:79], v[80:81], v[148:149] op_sel_hi:[1,0]
	v_cvt_pk_bf16_f32 v74, v74, v75
	v_mul_f32_e32 v80, 0xbfb8aa3b, v78
	v_mul_f32_e32 v81, 0xbfb8aa3b, v79
	v_exp_f32_e32 v80, v80
	v_exp_f32_e32 v81, v81
	v_add_f32_e32 v80, 1.0, v80
	v_add_f32_e32 v81, 1.0, v81
	v_rcp_f32_e32 v80, v80
	v_rcp_f32_e32 v81, v81
	s_nop 0
	v_pk_mul_f32 v[78:79], v[78:79], v[80:81]
	s_nop 0
	v_pk_mul_f32 v[76:77], v[76:77], v[78:79]
	s_nop 0
	v_cvt_pk_bf16_f32 v75, v76, v77
	v_mul_f32_e32 v76, 0xbfb8aa3b, v70
	v_mul_f32_e32 v77, 0xbfb8aa3b, v71
	v_exp_f32_e32 v76, v76
	v_exp_f32_e32 v77, v77
	v_add_f32_e32 v76, 1.0, v76
	v_add_f32_e32 v77, 1.0, v77
	v_rcp_f32_e32 v76, v76
	v_rcp_f32_e32 v77, v77
	s_nop 0
	v_pk_mul_f32 v[70:71], v[70:71], v[76:77]
	s_nop 0
	v_pk_mul_f32 v[66:67], v[66:67], v[70:71]
	v_pk_mul_f32 v[70:71], v[72:73], v[148:149] op_sel_hi:[1,0]
	v_cvt_pk_bf16_f32 v76, v66, v67
	v_mul_f32_e32 v72, 0xbfb8aa3b, v70
	v_mul_f32_e32 v73, 0xbfb8aa3b, v71
	v_exp_f32_e32 v72, v72
	v_exp_f32_e32 v73, v73
	v_or_b32_e32 v66, 48, v118
	v_mad_i64_i32 v[66:67], s[22:23], v66, s66, v[114:115]
	v_add_f32_e32 v72, 1.0, v72
	v_add_f32_e32 v73, 1.0, v73
	v_rcp_f32_e32 v72, v72
	v_rcp_f32_e32 v73, v73
	v_lshl_add_u64 v[66:67], v[66:67], 0, v[116:117]
	v_pk_mul_f32 v[70:71], v[70:71], v[72:73]
	s_nop 0
	v_pk_mul_f32 v[68:69], v[68:69], v[70:71]
	s_nop 0
	v_cvt_pk_bf16_f32 v77, v68, v69
	global_store_dwordx4 v[66:67], v[74:77], off
	v_mul_f32_e32 v66, 0xbfb8aa3b, v62
	v_mul_f32_e32 v67, 0xbfb8aa3b, v63
	v_exp_f32_e32 v66, v66
	v_exp_f32_e32 v67, v67
	v_add_f32_e32 v66, 1.0, v66
	v_add_f32_e32 v67, 1.0, v67
	v_rcp_f32_e32 v66, v66
	v_rcp_f32_e32 v67, v67
	s_nop 0
	v_pk_mul_f32 v[62:63], v[62:63], v[66:67]
	s_nop 0
	v_pk_mul_f32 v[58:59], v[58:59], v[62:63]
	v_pk_mul_f32 v[62:63], v[64:65], v[146:147] op_sel_hi:[1,0]
	v_cvt_pk_bf16_f32 v58, v58, v59
	v_mul_f32_e32 v64, 0xbfb8aa3b, v62
	v_mul_f32_e32 v65, 0xbfb8aa3b, v63
	v_exp_f32_e32 v64, v64
	v_exp_f32_e32 v65, v65
	v_add_f32_e32 v64, 1.0, v64
	v_add_f32_e32 v65, 1.0, v65
	v_rcp_f32_e32 v64, v64
	v_rcp_f32_e32 v65, v65
	s_nop 0
	v_pk_mul_f32 v[62:63], v[62:63], v[64:65]
	s_nop 0
	v_pk_mul_f32 v[60:61], v[60:61], v[62:63]
	s_nop 0
	v_cvt_pk_bf16_f32 v59, v60, v61
	v_mul_f32_e32 v60, 0xbfb8aa3b, v54
	v_mul_f32_e32 v61, 0xbfb8aa3b, v55
	v_exp_f32_e32 v60, v60
	v_exp_f32_e32 v61, v61
	v_add_f32_e32 v60, 1.0, v60
	v_add_f32_e32 v61, 1.0, v61
	v_rcp_f32_e32 v60, v60
	v_rcp_f32_e32 v61, v61
	s_nop 0
	v_pk_mul_f32 v[54:55], v[54:55], v[60:61]
	s_nop 0
	v_pk_mul_f32 v[50:51], v[50:51], v[54:55]
	v_pk_mul_f32 v[54:55], v[56:57], v[146:147] op_sel_hi:[1,0]
	v_cvt_pk_bf16_f32 v60, v50, v51
	v_mul_f32_e32 v56, 0xbfb8aa3b, v54
	v_mul_f32_e32 v57, 0xbfb8aa3b, v55
	v_exp_f32_e32 v56, v56
	v_exp_f32_e32 v57, v57
	v_add_u32_e32 v50, 0x80, v118
	v_mad_i64_i32 v[50:51], s[22:23], v50, s66, v[114:115]
	v_add_f32_e32 v56, 1.0, v56
	v_add_f32_e32 v57, 1.0, v57
	v_rcp_f32_e32 v56, v56
	v_rcp_f32_e32 v57, v57
	v_lshl_add_u64 v[50:51], v[50:51], 0, v[116:117]
	v_pk_mul_f32 v[54:55], v[54:55], v[56:57]
	s_nop 0
	v_pk_mul_f32 v[52:53], v[52:53], v[54:55]
	s_nop 0
	v_cvt_pk_bf16_f32 v61, v52, v53
	global_store_dwordx4 v[50:51], v[58:61], off
	v_mul_f32_e32 v50, 0xbfb8aa3b, v46
	v_mul_f32_e32 v51, 0xbfb8aa3b, v47
	v_exp_f32_e32 v50, v50
	v_exp_f32_e32 v51, v51
	v_add_f32_e32 v50, 1.0, v50
	v_add_f32_e32 v51, 1.0, v51
	v_rcp_f32_e32 v50, v50
	v_rcp_f32_e32 v51, v51
	s_nop 0
	v_pk_mul_f32 v[46:47], v[46:47], v[50:51]
	s_nop 0
	v_pk_mul_f32 v[42:43], v[42:43], v[46:47]
	v_pk_mul_f32 v[46:47], v[48:49], v[144:145] op_sel_hi:[1,0]
	v_cvt_pk_bf16_f32 v42, v42, v43
	v_mul_f32_e32 v48, 0xbfb8aa3b, v46
	v_mul_f32_e32 v49, 0xbfb8aa3b, v47
	v_exp_f32_e32 v48, v48
	v_exp_f32_e32 v49, v49
	v_add_f32_e32 v48, 1.0, v48
	v_add_f32_e32 v49, 1.0, v49
	v_rcp_f32_e32 v48, v48
	v_rcp_f32_e32 v49, v49
	s_nop 0
	v_pk_mul_f32 v[46:47], v[46:47], v[48:49]
	s_nop 0
	v_pk_mul_f32 v[44:45], v[44:45], v[46:47]
	s_nop 0
	v_cvt_pk_bf16_f32 v43, v44, v45
	v_mul_f32_e32 v44, 0xbfb8aa3b, v38
	v_mul_f32_e32 v45, 0xbfb8aa3b, v39
	v_exp_f32_e32 v44, v44
	v_exp_f32_e32 v45, v45
	v_add_f32_e32 v44, 1.0, v44
	v_add_f32_e32 v45, 1.0, v45
	v_rcp_f32_e32 v44, v44
	v_rcp_f32_e32 v45, v45
	s_nop 0
	v_pk_mul_f32 v[38:39], v[38:39], v[44:45]
	s_nop 0
	v_pk_mul_f32 v[34:35], v[34:35], v[38:39]
	v_pk_mul_f32 v[38:39], v[40:41], v[144:145] op_sel_hi:[1,0]
	v_cvt_pk_bf16_f32 v44, v34, v35
	v_mul_f32_e32 v40, 0xbfb8aa3b, v38
	v_mul_f32_e32 v41, 0xbfb8aa3b, v39
	v_exp_f32_e32 v40, v40
	v_exp_f32_e32 v41, v41
	v_add_u32_e32 v34, 0x90, v118
	v_mad_i64_i32 v[34:35], s[22:23], v34, s66, v[114:115]
	v_add_f32_e32 v40, 1.0, v40
	v_add_f32_e32 v41, 1.0, v41
	v_rcp_f32_e32 v40, v40
	v_rcp_f32_e32 v41, v41
	v_lshl_add_u64 v[34:35], v[34:35], 0, v[116:117]
	v_pk_mul_f32 v[38:39], v[38:39], v[40:41]
	s_nop 0
	v_pk_mul_f32 v[36:37], v[36:37], v[38:39]
	s_nop 0
	v_cvt_pk_bf16_f32 v45, v36, v37
	global_store_dwordx4 v[34:35], v[42:45], off
	s_waitcnt vmcnt(6)
	v_add_f32_e32 v214, v214, v215
	v_add_f32_e32 v216, v216, v217
	v_add_f32_e32 v214, v214, v216
	v_add_f32_e32 v224, v224, v225
	v_add_f32_e32 v226, v226, v227
	v_add_f32_e32 v224, v224, v226
	v_mov_b32_e32 v215, v214
	v_mov_b32_e32 v225, v224
	s_nop 1
	v_permlane16_swap_b32_e32 v214, v215
	v_permlane16_swap_b32_e32 v224, v225
	v_add_f32_e32 v214, v214, v215
	v_add_f32_e32 v224, v224, v225
	v_mov_b32_e32 v215, v214
	v_mov_b32_e32 v225, v224
	s_nop 1
	v_permlane32_swap_b32_e32 v214, v215
	v_permlane32_swap_b32_e32 v224, v225
	v_add_f32_e32 v214, v214, v215
	v_add_f32_e32 v224, v224, v225
	v_fmamk_f32 v214, v214, 0x3a800000, v213
	v_fmamk_f32 v224, v224, 0x3a800000, v213
	v_rsq_f32_e32 v142, v214
	v_rsq_f32_e32 v140, v224
	s_nop 0
	v_pk_mul_f32 v[30:31], v[30:31], v[142:143] op_sel_hi:[1,0]
	v_pk_mul_f32 v[26:27], v[26:27], v[142:143] op_sel_hi:[1,0]
	v_pk_mul_f32 v[28:29], v[28:29], v[142:143] op_sel_hi:[1,0]
	v_pk_mul_f32 v[22:23], v[22:23], v[142:143] op_sel_hi:[1,0]
	v_pk_mul_f32 v[18:19], v[18:19], v[142:143] op_sel_hi:[1,0]
	v_pk_mul_f32 v[20:21], v[20:21], v[142:143] op_sel_hi:[1,0]
	v_pk_mul_f32 v[14:15], v[14:15], v[140:141] op_sel_hi:[1,0]
	v_pk_mul_f32 v[10:11], v[10:11], v[140:141] op_sel_hi:[1,0]
	v_pk_mul_f32 v[12:13], v[12:13], v[140:141] op_sel_hi:[1,0]
	v_pk_mul_f32 v[6:7], v[6:7], v[140:141] op_sel_hi:[1,0]
	v_pk_mul_f32 v[2:3], v[2:3], v[140:141] op_sel_hi:[1,0]
	v_pk_mul_f32 v[4:5], v[4:5], v[140:141] op_sel_hi:[1,0]
	v_mul_f32_e32 v34, 0xbfb8aa3b, v30
	v_mul_f32_e32 v35, 0xbfb8aa3b, v31
	v_exp_f32_e32 v34, v34
	v_exp_f32_e32 v35, v35
	v_add_f32_e32 v34, 1.0, v34
	v_add_f32_e32 v35, 1.0, v35
	v_rcp_f32_e32 v34, v34
	v_rcp_f32_e32 v35, v35
	s_nop 0
	v_pk_mul_f32 v[30:31], v[30:31], v[34:35]
	s_nop 0
	v_pk_mul_f32 v[26:27], v[26:27], v[30:31]
	v_pk_mul_f32 v[30:31], v[32:33], v[142:143] op_sel_hi:[1,0]
	v_cvt_pk_bf16_f32 v26, v26, v27
	v_mul_f32_e32 v32, 0xbfb8aa3b, v30
	v_mul_f32_e32 v33, 0xbfb8aa3b, v31
	v_exp_f32_e32 v32, v32
	v_exp_f32_e32 v33, v33
	v_add_f32_e32 v32, 1.0, v32
	v_add_f32_e32 v33, 1.0, v33
	v_rcp_f32_e32 v32, v32
	v_rcp_f32_e32 v33, v33
	s_nop 0
	v_pk_mul_f32 v[30:31], v[30:31], v[32:33]
	s_nop 0
	v_pk_mul_f32 v[28:29], v[28:29], v[30:31]
	s_nop 0
	v_cvt_pk_bf16_f32 v27, v28, v29
	v_mul_f32_e32 v28, 0xbfb8aa3b, v22
	v_mul_f32_e32 v29, 0xbfb8aa3b, v23
	v_exp_f32_e32 v28, v28
	v_exp_f32_e32 v29, v29
	v_add_f32_e32 v28, 1.0, v28
	v_add_f32_e32 v29, 1.0, v29
	v_rcp_f32_e32 v28, v28
	v_rcp_f32_e32 v29, v29
	s_nop 0
	v_pk_mul_f32 v[22:23], v[22:23], v[28:29]
	s_nop 0
	v_pk_mul_f32 v[18:19], v[18:19], v[22:23]
	v_pk_mul_f32 v[22:23], v[24:25], v[142:143] op_sel_hi:[1,0]
	v_cvt_pk_bf16_f32 v28, v18, v19
	v_mul_f32_e32 v24, 0xbfb8aa3b, v22
	v_mul_f32_e32 v25, 0xbfb8aa3b, v23
	v_exp_f32_e32 v24, v24
	v_exp_f32_e32 v25, v25
	v_add_u32_e32 v18, 0xa0, v118
	v_mad_i64_i32 v[18:19], s[22:23], v18, s66, v[114:115]
	v_add_f32_e32 v24, 1.0, v24
	v_add_f32_e32 v25, 1.0, v25
	v_rcp_f32_e32 v24, v24
	v_rcp_f32_e32 v25, v25
	v_lshl_add_u64 v[18:19], v[18:19], 0, v[116:117]
	v_pk_mul_f32 v[22:23], v[22:23], v[24:25]
	s_nop 0
	v_pk_mul_f32 v[20:21], v[20:21], v[22:23]
	s_nop 0
	v_cvt_pk_bf16_f32 v29, v20, v21
	global_store_dwordx4 v[18:19], v[26:29], off
	v_mul_f32_e32 v18, 0xbfb8aa3b, v14
	v_mul_f32_e32 v19, 0xbfb8aa3b, v15
	v_exp_f32_e32 v18, v18
	v_exp_f32_e32 v19, v19
	v_add_f32_e32 v18, 1.0, v18
	v_add_f32_e32 v19, 1.0, v19
	v_rcp_f32_e32 v18, v18
	v_rcp_f32_e32 v19, v19
	s_nop 0
	v_pk_mul_f32 v[14:15], v[14:15], v[18:19]
	s_nop 0
	v_pk_mul_f32 v[10:11], v[10:11], v[14:15]
	v_pk_mul_f32 v[14:15], v[16:17], v[140:141] op_sel_hi:[1,0]
	v_cvt_pk_bf16_f32 v10, v10, v11
	v_mul_f32_e32 v16, 0xbfb8aa3b, v14
	v_mul_f32_e32 v17, 0xbfb8aa3b, v15
	v_exp_f32_e32 v16, v16
	v_exp_f32_e32 v17, v17
	v_add_f32_e32 v16, 1.0, v16
	v_add_f32_e32 v17, 1.0, v17
	v_rcp_f32_e32 v16, v16
	v_rcp_f32_e32 v17, v17
	s_nop 0
	v_pk_mul_f32 v[14:15], v[14:15], v[16:17]
	s_nop 0
	v_pk_mul_f32 v[12:13], v[12:13], v[14:15]
	s_nop 0
	v_cvt_pk_bf16_f32 v11, v12, v13
	v_mul_f32_e32 v12, 0xbfb8aa3b, v6
	v_mul_f32_e32 v13, 0xbfb8aa3b, v7
	v_exp_f32_e32 v12, v12
	v_exp_f32_e32 v13, v13
	v_add_f32_e32 v12, 1.0, v12
	v_add_f32_e32 v13, 1.0, v13
	v_rcp_f32_e32 v12, v12
	v_rcp_f32_e32 v13, v13
	s_nop 0
	v_pk_mul_f32 v[6:7], v[6:7], v[12:13]
	s_nop 0
	v_pk_mul_f32 v[2:3], v[2:3], v[6:7]
	v_pk_mul_f32 v[6:7], v[8:9], v[140:141] op_sel_hi:[1,0]
	v_cvt_pk_bf16_f32 v12, v2, v3
	v_mul_f32_e32 v8, 0xbfb8aa3b, v6
	v_mul_f32_e32 v9, 0xbfb8aa3b, v7
	v_exp_f32_e32 v8, v8
	v_exp_f32_e32 v9, v9
	v_add_u32_e32 v2, 0xb0, v118
	v_mad_i64_i32 v[2:3], s[22:23], v2, s66, v[114:115]
	v_add_f32_e32 v8, 1.0, v8
	v_add_f32_e32 v9, 1.0, v9
	v_rcp_f32_e32 v8, v8
	v_rcp_f32_e32 v9, v9
	v_lshl_add_u64 v[2:3], v[2:3], 0, v[116:117]
	s_mov_b64 s[22:23], -1
	v_pk_mul_f32 v[6:7], v[6:7], v[8:9]
	s_nop 0
	v_pk_mul_f32 v[4:5], v[4:5], v[6:7]
	s_nop 0
	v_cvt_pk_bf16_f32 v13, v4, v5
	global_store_dwordx4 v[2:3], v[10:13], off
	s_cbranch_vccnz .LBB0_1229
	s_andn2_b64 vcc, exec, s[2:3]
	s_cbranch_vccnz .LBB0_1228
	s_barrier
	s_branch .LBB0_1228
